# opt21: attention loops: 152 more redundant v_max(x,x) removed where the temp is dead after its single use (hazard distances re-checked)
# baseline (speedup 1.0000x reference)
; #define MFMA16(a, b, c) __builtin_amdgcn_mfma_f32_16x16x32_f16((a), (b), (c), 0, 0, 0)
; __device__ __forceinline__ float shx(float v, int m) { return __shfl_xor(v, m); }
;     ...
;     for (int it = 0; it < nit; ++it) {
;         const int kbN = kbof((it + 1 < nit) ? it + 1 : it);
;         const int nbA = kbN >> 5, nbB = (nbA + 1 <= maxblk) ? nbA + 1 : maxblk;
;         const f32x4 z = {0.f, 0.f, 0.f, 0.f};
; #pragma unroll
;         for (int s_ = 0; s_ < NS; ++s_) {
;             f32x4 s[4];
; #pragma unroll
;             for (int t = 0; t < 4; ++t) { s[t] = MFMA16(ka[2 * t], qf[s_][0], z); s[t] = MFMA16(ka[2 * t + 1], qf[s_][1], s[t]); }
;             if (s_ == NS - 1) {
;                 const half_t* kpA = kf + (size_t)nbA * 2048; const half_t* kpB = kf + (size_t)nbB * 2048;
; #pragma unroll
;                 for (int i = 0; i < 4; ++i) { ka[i] = *(const half8*)(kpA + i * 512); ka[4 + i] = *(const half8*)(kpB + i * 512); }
;             }
;             if (MODE != 1) {
;                 float mx = -1e30f;
; #pragma unroll
;                 for (int t = 0; t < 4; ++t)
; #pragma unroll
;                     for (int r = 0; r < 4; ++r) { if (valid(s_, kbA + 16 * t + 4 * g + r)) mx = fmaxf(mx, s[t][r]); }
;                 if (__ballot(mx > m[s_] + RESC_THR) != 0ull) {
;                     mx = fmaxf(mx, shx(mx, 16)); mx = fmaxf(mx, shx(mx, 32));
;                     const float mn = fmaxf(m[s_], mx); const float corr = __builtin_amdgcn_exp2f(m[s_] - mn); m[s_] = mn; l[s_] = l[s_] * corr;
;                     if (PV) {
; #pragma unroll
;                         for (int dt = 0; dt < 4; ++dt) o[s_][dt] = o[s_][dt] * corr;
;                     }
;                 }
;             }
;             float p[4][4]; float ps = 0.f;
; #pragma unroll
;             for (int t = 0; t < 4; ++t)
; #pragma unroll
;                 for (int r = 0; r < 4; ++r) { p[t][r] = valid(s_, kbA + 16 * t + 4 * g + r) ? __builtin_amdgcn_exp2f(s[t][r] - m[s_]) : 0.f; if (MODE == 1) p[t][r] *= l[s_]; ps += p[t][r]; }
;             if (MODE != 1) l[s_] = l[s_] + ps;
; __device__ __forceinline__ void a_unit(const ACtx& X, int b, int t0, float* ldsw, int lane) {
;     ...
;         auto valid = [&](int s_, int n) { return n <= nval[s_]; };
.LBB0_694:
	s_waitcnt vmcnt(0) lgkmcnt(0)
	v_mfma_f32_16x16x32_f16 v[50:53], v[18:21], v[2:5], 0
	v_or_b32_e32 v91, s33, v166
	v_cmp_gt_i32_e64 s[10:11], v91, v122
	v_cmp_lt_i32_e64 s[12:13], v91, v122
	v_mfma_f32_16x16x32_f16 v[54:57], v[42:45], v[6:9], v[50:53]
	v_or_b32_e32 v97, 2, v91
	v_cmp_gt_i32_e64 s[14:15], v97, v122
	v_or_b32_e32 v100, 3, v91
	v_cmp_gt_i32_e64 s[16:17], v100, v122
	v_or_b32_e32 v101, 16, v91
	s_nop 2
	v_max_f32_e32 v50, 0xf149f2ca, v54
	v_cndmask_b32_e64 v59, v50, v172, s[10:11]
	v_mfma_f32_16x16x32_f16 v[50:53], v[46:49], v[2:5], 0
	v_max_f32_e32 v58, v59, v55
	v_cndmask_b32_e64 v62, v59, v58, s[12:13]
	v_mfma_f32_16x16x32_f16 v[58:61], v[38:41], v[6:9], v[50:53]
	v_max_f32_e32 v67, v57, v57
	v_cmp_gt_i32_e64 s[18:19], v101, v122
	v_or_b32_e32 v102, 17, v91
	s_nop 0
	s_nop 0
	v_max_f32_e32 v63, v62, v56
	v_mfma_f32_16x16x32_f16 v[50:53], v[22:25], v[2:5], 0
	v_cndmask_b32_e64 v66, v63, v62, s[14:15]
	v_cmp_gt_i32_e64 s[22:23], v102, v122
	v_mfma_f32_16x16x32_f16 v[62:65], v[26:29], v[6:9], v[50:53]
	v_or_b32_e32 v99, 18, v91
	v_cmp_gt_i32_e64 s[20:21], v99, v122
	v_or_b32_e32 v98, 19, v91
	s_nop 0
	s_nop 0
	v_max_f32_e32 v50, v66, v67
	v_cndmask_b32_e64 v66, v50, v66, s[16:17]
	v_max_f32_e32 v67, v66, v58
	v_cndmask_b32_e64 v66, v67, v66, s[18:19]
	v_max_f32_e32 v67, v66, v59
	v_cndmask_b32_e64 v66, v67, v66, s[22:23]
	v_max_f32_e32 v67, v66, v60
	v_cndmask_b32_e64 v66, v67, v66, s[20:21]
	v_max_f32_e32 v67, v66, v61
	v_cmp_gt_i32_e64 s[26:27], v98, v122
	v_or_b32_e32 v96, 32, v91
	s_nop 0
	v_cndmask_b32_e64 v66, v67, v66, s[26:27]
	v_max_f32_e32 v67, v66, v62
	v_cmp_gt_i32_e64 s[24:25], v96, v122
	v_or_b32_e32 v95, 33, v91
	s_nop 0
	v_cndmask_b32_e64 v66, v67, v66, s[24:25]
	v_mfma_f32_16x16x32_f16 v[50:53], v[30:33], v[2:5], 0
	v_max_f32_e32 v67, v66, v63
	v_cmp_gt_i32_e64 s[30:31], v95, v122
	v_or_b32_e32 v94, 34, v91
	s_nop 0
	v_cndmask_b32_e64 v66, v67, v66, s[30:31]
	v_max_f32_e32 v67, v66, v64
	v_cmp_gt_i32_e64 s[28:29], v94, v122
	v_mfma_f32_16x16x32_f16 v[50:53], v[34:37], v[6:9], v[50:53]
	v_or_b32_e32 v93, 35, v91
	v_cndmask_b32_e64 v66, v67, v66, s[28:29]
	v_max_f32_e32 v67, v66, v65
	v_cmp_gt_i32_e64 s[36:37], v93, v122
	v_or_b32_e32 v92, 48, v91
	s_nop 0
	s_nop 0
	v_cndmask_b32_e64 v66, v67, v66, s[36:37]
	v_max_f32_e32 v67, v66, v50
	v_cmp_gt_i32_e64 s[34:35], v92, v122
	v_or_b32_e32 v90, 49, v91
	s_nop 0
	v_cndmask_b32_e64 v66, v67, v66, s[34:35]
	v_max_f32_e32 v67, v66, v51
	v_cmp_gt_i32_e64 s[40:41], v90, v122
	v_or_b32_e32 v89, 50, v91
	s_nop 0
	v_cndmask_b32_e64 v66, v67, v66, s[40:41]
	v_max_f32_e32 v67, v66, v52
	v_cmp_gt_i32_e64 s[38:39], v89, v122
	v_or_b32_e32 v88, 51, v91
	v_max_f32_e32 v68, v53, v53
	v_cndmask_b32_e64 v66, v67, v66, s[38:39]
	v_max_f32_e32 v67, v66, v68
	v_cmp_gt_i32_e64 s[42:43], v88, v122
	s_nop 1
	v_cndmask_b32_e64 v66, v67, v66, s[42:43]
	v_add_f32_e32 v67, 0x41400000, v128
	v_cmp_gt_f32_e32 vcc, v66, v67
	s_cbranch_vccz .LBB0_696
	v_and_b32_e32 v68, 64, v204
	v_xor_b32_e32 v67, 16, v204
	v_add_u32_e32 v68, 64, v68
	v_cmp_lt_i32_e32 vcc, v67, v68
	v_mov_b32_e32 v85, v129
	s_nop 0
	v_cndmask_b32_e32 v67, v204, v67, vcc
	v_lshlrev_b32_e32 v67, 2, v67
	ds_bpermute_b32 v67, v67, v66
	v_max_f32_e32 v66, v66, v66
	s_waitcnt lgkmcnt(0)
	v_max_f32_e32 v67, v67, v67
	v_max_f32_e32 v66, v66, v67
	v_xor_b32_e32 v67, 32, v204
	v_cmp_lt_i32_e32 vcc, v67, v68
	s_nop 1
	v_cndmask_b32_e32 v67, v204, v67, vcc
	v_lshlrev_b32_e32 v67, 2, v67
	ds_bpermute_b32 v67, v67, v66
	s_waitcnt lgkmcnt(0)
	v_max3_f32 v84, v128, v66, v67
	v_sub_f32_e32 v66, v128, v84
	v_exp_f32_e32 v66, v66
	v_mov_b64_e32 v[128:129], v[84:85]
	v_mul_f32_e32 v82, v82, v66
	s_branch .LBB0_697

; #define MFMA16(a, b, c) __builtin_amdgcn_mfma_f32_16x16x32_f16((a), (b), (c), 0, 0, 0)
; __device__ __forceinline__ float shx(float v, int m) { return __shfl_xor(v, m); }
;     ...
;             for (int t = 0; t < 4; ++t) { s[t] = MFMA16(ka[2 * t], qf[s_][0], z); s[t] = MFMA16(ka[2 * t + 1], qf[s_][1], s[t]); }
;             if (s_ == NS - 1) {
;                 const half_t* kpA = kf + (size_t)nbA * 2048; const half_t* kpB = kf + (size_t)nbB * 2048;
; #pragma unroll
;                 for (int i = 0; i < 4; ++i) { ka[i] = *(const half8*)(kpA + i * 512); ka[4 + i] = *(const half8*)(kpB + i * 512); }
;             }
;             if (MODE != 1) {
;                 float mx = -1e30f;
; #pragma unroll
;                 for (int t = 0; t < 4; ++t)
; #pragma unroll
;                     for (int r = 0; r < 4; ++r) { if (valid(s_, kbA + 16 * t + 4 * g + r)) mx = fmaxf(mx, s[t][r]); }
;                 if (__ballot(mx > m[s_] + RESC_THR) != 0ull) {
;                     mx = fmaxf(mx, shx(mx, 16)); mx = fmaxf(mx, shx(mx, 32));
;                     const float mn = fmaxf(m[s_], mx); const float corr = __builtin_amdgcn_exp2f(m[s_] - mn); m[s_] = mn; l[s_] = l[s_] * corr;
;                     if (PV) {
; #pragma unroll
;                         for (int dt = 0; dt < 4; ++dt) o[s_][dt] = o[s_][dt] * corr;
;                     }
;                 }
;             }
.LBB0_697:
	v_mfma_f32_16x16x32_f16 v[18:21], v[18:21], v[10:13], 0
	s_add_i32 s94, s44, 1
	s_cmp_lt_u32 s94, s88
	s_cselect_b32 s33, s94, s44
	v_mfma_f32_16x16x32_f16 v[78:81], v[42:45], v[14:17], v[18:21]
	s_lshl_b32 s33, s33, 6
	s_lshr_b32 s84, s33, 5
	s_min_u32 s46, s84, 30
	v_mfma_f32_16x16x32_f16 v[18:21], v[46:49], v[10:13], 0
	s_lshl_b64 s[44:45], s[84:85], 12
	s_lshl_b32 s84, s46, 12
	v_lshl_add_u64 v[104:105], v[126:127], 0, s[44:45]
	v_mfma_f32_16x16x32_f16 v[74:77], v[38:41], v[14:17], v[18:21]
	v_lshl_add_u64 v[106:107], v[126:127], 0, s[84:85]
	s_movk_i32 s44, 0x1000
	v_mfma_f32_16x16x32_f16 v[18:21], v[22:25], v[10:13], 0
	v_max_f32_e32 v85, 0xf149f2ca, v78
	v_cmp_lt_i32_e64 s[46:47], v91, v124
	v_cmp_gt_i32_e64 s[48:49], v97, v124
	v_mfma_f32_16x16x32_f16 v[70:73], v[26:29], v[14:17], v[18:21]
	v_cmp_gt_i32_e64 s[50:51], v100, v124
	v_cmp_gt_i32_e64 s[52:53], v101, v124
	v_max_f32_e32 v97, v75, v75
	v_mfma_f32_16x16x32_f16 v[18:21], v[30:33], v[10:13], 0
	v_cmp_gt_i32_e64 s[54:55], v102, v124
	v_cmp_gt_i32_e64 s[56:57], v99, v124
	v_cmp_gt_i32_e64 s[58:59], v98, v124
	v_mfma_f32_16x16x32_f16 v[66:69], v[34:37], v[14:17], v[18:21]
	v_add_co_u32_e32 v34, vcc, s44, v106
	v_cmp_gt_i32_e64 s[44:45], v91, v124
	s_nop 0
	v_addc_co_u32_e32 v35, vcc, 0, v107, vcc
	flat_load_dwordx4 v[18:21], v[104:105]
	flat_load_dwordx4 v[22:25], v[34:35]
	flat_load_dwordx4 v[42:45], v[104:105] offset:1024
	flat_load_dwordx4 v[26:29], v[34:35] offset:1024
	flat_load_dwordx4 v[46:49], v[104:105] offset:2048
	flat_load_dwordx4 v[30:33], v[34:35] offset:2048
	flat_load_dwordx4 v[38:41], v[104:105] offset:3072
	s_nop 0
	flat_load_dwordx4 v[34:37], v[34:35] offset:3072
	v_cndmask_b32_e64 v85, v85, v172, s[44:45]
	v_max_f32_e32 v91, v85, v79
	v_cndmask_b32_e64 v85, v85, v91, s[46:47]
	v_max_f32_e32 v91, v85, v80
	v_cndmask_b32_e64 v85, v91, v85, s[48:49]
	v_max_f32_e32 v91, v85, v81
	v_cndmask_b32_e64 v85, v91, v85, s[50:51]
	v_max_f32_e32 v91, v85, v74
	v_cndmask_b32_e64 v85, v91, v85, s[52:53]
	v_max_f32_e32 v91, v85, v97
	v_cndmask_b32_e64 v85, v91, v85, s[54:55]
	v_max_f32_e32 v91, v85, v76
	v_cndmask_b32_e64 v85, v91, v85, s[56:57]
	v_max_f32_e32 v97, v77, v77
	v_max_f32_e32 v91, v85, v97
	v_cndmask_b32_e64 v85, v91, v85, s[58:59]
	v_cmp_gt_i32_e64 s[60:61], v96, v124
	v_max_f32_e32 v96, v70, v70
	v_max_f32_e32 v91, v85, v96
	v_cndmask_b32_e64 v85, v91, v85, s[60:61]
	v_cmp_gt_i32_e64 s[62:63], v95, v124
	v_max_f32_e32 v95, v71, v71
	v_max_f32_e32 v91, v85, v95
	v_cndmask_b32_e64 v85, v91, v85, s[62:63]
	v_cmp_gt_i32_e64 s[64:65], v94, v124
	v_max_f32_e32 v94, v72, v72
	v_max_f32_e32 v91, v85, v94
	v_cndmask_b32_e64 v85, v91, v85, s[64:65]
	v_cmp_gt_i32_e64 s[66:67], v93, v124
	v_max_f32_e32 v93, v73, v73
	v_max_f32_e32 v91, v85, v93
	v_cndmask_b32_e64 v85, v91, v85, s[66:67]
	v_cmp_gt_i32_e64 s[68:69], v92, v124
	v_max_f32_e32 v92, v66, v66
	v_max_f32_e32 v91, v85, v92
	v_cndmask_b32_e64 v85, v91, v85, s[68:69]
	v_cmp_gt_i32_e64 s[70:71], v90, v124
	v_max_f32_e32 v91, v67, v67
	v_max_f32_e32 v90, v85, v91
	v_cndmask_b32_e64 v85, v90, v85, s[70:71]
	v_cmp_gt_i32_e64 s[72:73], v89, v124
	v_max_f32_e32 v90, v68, v68
	v_max_f32_e32 v89, v85, v90
	v_cndmask_b32_e64 v85, v89, v85, s[72:73]
	v_cmp_gt_i32_e64 s[74:75], v88, v124
	v_max_f32_e32 v89, v69, v69
	v_max_f32_e32 v88, v85, v89
	v_cndmask_b32_e64 v85, v88, v85, s[74:75]
	v_add_f32_e32 v88, 0x41400000, v129
	v_cmp_gt_f32_e32 vcc, v85, v88
	s_cbranch_vccz .LBB0_699
	v_and_b32_e32 v89, 64, v204
	v_xor_b32_e32 v88, 16, v204
	v_add_u32_e32 v89, 64, v89
	v_cmp_lt_i32_e32 vcc, v88, v89
	s_nop 1
	v_cndmask_b32_e32 v88, v204, v88, vcc
	v_lshlrev_b32_e32 v88, 2, v88
	ds_bpermute_b32 v88, v88, v85
	v_max_f32_e32 v85, v85, v85
	s_waitcnt lgkmcnt(0)
	v_max_f32_e32 v88, v88, v88
	v_max_f32_e32 v85, v85, v88
	v_xor_b32_e32 v88, 32, v204
	v_cmp_lt_i32_e32 vcc, v88, v89
	s_nop 1
	v_cndmask_b32_e32 v88, v204, v88, vcc
	v_lshlrev_b32_e32 v88, 2, v88
	ds_bpermute_b32 v88, v88, v85
	s_waitcnt lgkmcnt(0)
	v_max3_f32 v85, v129, v85, v88
	v_sub_f32_e32 v88, v129, v85
	v_exp_f32_e32 v88, v88
	v_mov_b32_e32 v129, v85
	v_mul_f32_e32 v83, v83, v88
	s_branch .LBB0_700

; #define MFMA16(a, b, c) __builtin_amdgcn_mfma_f32_16x16x32_f16((a), (b), (c), 0, 0, 0)
; __device__ __forceinline__ float shx(float v, int m) { return __shfl_xor(v, m); }
; template <class KB>
; __device__ __forceinline__ void sel_run(int nit, KB kbof, const half8 (&qf)[2][2], const unsigned char* kf, const unsigned char* vf, const int (&tqs)[2], int qq,
;                                         f32x4 (&o)[2][4], float (&m)[2], float (&l)[2], int g) {
;     ...
;         half8 kh[8];
; #pragma unroll
;         for (int i = 0; i < 8; ++i) kh[i] = fp8x8_to_half8(ka[i]);
;         {
;             const unsigned char* kp = kf + (size_t)(kbN >> 5) * 2048;
; #pragma unroll
;             for (int i = 0; i < 8; ++i) ka[i] = *(const u32x2*)(kp + i * 512);
;         }
;         const f32x4 z = {0.f, 0.f, 0.f, 0.f};
;         f32x4 s[2][4];
; #pragma unroll
;         for (int s_ = 0; s_ < 2; ++s_)
;             if (need[s_]) {
; #pragma unroll
;                 for (int t = 0; t < 4; ++t) { s[s_][t] = MFMA16(kh[2 * t], qf[s_][0], z); s[s_][t] = MFMA16(kh[2 * t + 1], qf[s_][1], s[s_][t]); }
;             }
;         half8 vh[8];
; #pragma unroll
;         for (int i = 0; i < 8; ++i) vh[i] = fp8x8_to_half8(va[i]);
;         {
;             const unsigned char* vp = vf + (size_t)(kbN >> 5) * 2048;
; #pragma unroll
;             for (int i = 0; i < 8; ++i) va[i] = *(const u32x2*)(vp + i * 512);
;         }
; #pragma unroll
;         for (int s_ = 0; s_ < 2; ++s_)
;             if (need[s_]) {
;                 float p[4][4]; float mx = -1e30f;
;                 const int klim = selq[s_] ? tqs[s_] - kbA - 4 * g : -1;
; #pragma unroll
;                 for (int t = 0; t < 4; ++t)
; #pragma unroll
;                     for (int r = 0; r < 4; ++r) { if (16 * t + r <= klim) mx = fmaxf(mx, s[s_][t][r]); }
;                 if (__ballot(mx > m[s_] + RESC_THR) != 0ull) {
;                     mx = fmaxf(mx, shx(mx, 16)); mx = fmaxf(mx, shx(mx, 32));
;                     const float mn = fmaxf(m[s_], mx); const float corr = __builtin_amdgcn_exp2f(m[s_] - mn); m[s_] = mn;
;                     l[s_] = l[s_] * corr;
; #pragma unroll
;                     for (int dt = 0; dt < 4; ++dt) o[s_][dt] = o[s_][dt] * corr;
;                 }
.LBB0_934:
	s_waitcnt vmcnt(8)
	v_cvt_scalef32_pk_f16_fp8 v90, v122, 1.0
	v_cvt_scalef32_pk_f16_fp8 v91, v122, 1.0 op_sel:[1,0,0]
	v_cvt_scalef32_pk_f16_fp8 v92, v123, 1.0
	v_cvt_scalef32_pk_f16_fp8 v93, v123, 1.0 op_sel:[1,0,0]
	v_lshl_add_u64 v[122:123], v[120:121], 0, s[84:85]
	v_cvt_scalef32_pk_f16_fp8 v102, v188, 1.0
	v_cvt_scalef32_pk_f16_fp8 v103, v188, 1.0 op_sel:[1,0,0]
	v_cvt_scalef32_pk_f16_fp8 v104, v189, 1.0
	v_cvt_scalef32_pk_f16_fp8 v105, v189, 1.0 op_sel:[1,0,0]
	v_cvt_scalef32_pk_f16_fp8 v94, v186, 1.0
	v_cvt_scalef32_pk_f16_fp8 v95, v186, 1.0 op_sel:[1,0,0]
	v_cvt_scalef32_pk_f16_fp8 v96, v187, 1.0
	v_cvt_scalef32_pk_f16_fp8 v97, v187, 1.0 op_sel:[1,0,0]
	v_cvt_scalef32_pk_f16_fp8 v86, v184, 1.0
	v_cvt_scalef32_pk_f16_fp8 v87, v184, 1.0 op_sel:[1,0,0]
	v_cvt_scalef32_pk_f16_fp8 v88, v185, 1.0
	v_cvt_scalef32_pk_f16_fp8 v89, v185, 1.0 op_sel:[1,0,0]
	v_cvt_scalef32_pk_f16_fp8 v82, v180, 1.0
	v_cvt_scalef32_pk_f16_fp8 v83, v180, 1.0 op_sel:[1,0,0]
	v_cvt_scalef32_pk_f16_fp8 v84, v181, 1.0
	v_cvt_scalef32_pk_f16_fp8 v85, v181, 1.0 op_sel:[1,0,0]
	v_cvt_scalef32_pk_f16_fp8 v110, v158, 1.0
	v_cvt_scalef32_pk_f16_fp8 v111, v158, 1.0 op_sel:[1,0,0]
	v_cvt_scalef32_pk_f16_fp8 v112, v159, 1.0
	v_cvt_scalef32_pk_f16_fp8 v113, v159, 1.0 op_sel:[1,0,0]
	v_cvt_scalef32_pk_f16_fp8 v106, v156, 1.0
	v_cvt_scalef32_pk_f16_fp8 v107, v156, 1.0 op_sel:[1,0,0]
	v_cvt_scalef32_pk_f16_fp8 v108, v157, 1.0
	v_cvt_scalef32_pk_f16_fp8 v109, v157, 1.0 op_sel:[1,0,0]
	v_cvt_scalef32_pk_f16_fp8 v98, v126, 1.0
	v_cvt_scalef32_pk_f16_fp8 v99, v126, 1.0 op_sel:[1,0,0]
	v_cvt_scalef32_pk_f16_fp8 v100, v127, 1.0
	v_cvt_scalef32_pk_f16_fp8 v101, v127, 1.0 op_sel:[1,0,0]
	global_load_dwordx2 v[188:189], v[122:123], off
	global_load_dwordx2 v[186:187], v[122:123], off offset:512
	global_load_dwordx2 v[184:185], v[122:123], off offset:1024
	global_load_dwordx2 v[180:181], v[122:123], off offset:1536
	global_load_dwordx2 v[158:159], v[122:123], off offset:2048
	global_load_dwordx2 v[156:157], v[122:123], off offset:2560
	global_load_dwordx2 v[126:127], v[122:123], off offset:3072
	s_nop 0
	global_load_dwordx2 v[122:123], v[122:123], off offset:3584
	s_add_i32 s100, s12, 64
	s_lshr_b32 s33, s13, 8
	s_andn2_b64 vcc, exec, s[10:11]
	v_subrev_u32_e32 v226, s12, v213
	s_cbranch_vccnz .LBB0_938
	s_cmp_le_u32 s100, s93
	s_cbranch_scc1 .Lsel_fast0
	v_lshrrev_b32_e64 v227, v192, s33
	v_and_b32_e32 v227, 1, v227
	v_add_u32_e32 v228, v226, v223
	v_cmp_eq_u32_e32 vcc, 1, v227
	v_max_f32_e32 v230, v63, v63
	s_nop 0
	v_cndmask_b32_e32 v227, -1, v228, vcc
	v_max_f32_e32 v228, 0xf149f2ca, v54
	v_cmp_gt_i32_e64 s[42:43], 0, v227
	v_cmp_gt_i32_e64 s[40:41], 1, v227
	v_cmp_gt_i32_e64 s[38:39], 2, v227
	v_cndmask_b32_e64 v228, v228, v172, s[42:43]
	v_max_f32_e32 v229, v228, v55
	v_cndmask_b32_e64 v228, v229, v228, s[40:41]
	v_max_f32_e32 v229, v228, v56
	v_cndmask_b32_e64 v228, v229, v228, s[38:39]
	v_max_f32_e32 v229, v228, v57
	v_cmp_gt_i32_e64 s[36:37], 3, v227
	v_cmp_gt_i32_e64 s[34:35], 16, v227
	v_cmp_gt_i32_e64 s[30:31], 17, v227
	v_cndmask_b32_e64 v228, v229, v228, s[36:37]
	v_max_f32_e32 v229, v228, v62
	v_cndmask_b32_e64 v228, v229, v228, s[34:35]
	v_max_f32_e32 v229, v228, v230
	v_cndmask_b32_e64 v228, v229, v228, s[30:31]
	v_max_f32_e32 v229, v228, v64
	v_cmp_gt_i32_e64 s[28:29], 18, v227
	v_cmp_gt_i32_e64 s[26:27], 19, v227
	s_nop 0
	v_cndmask_b32_e64 v228, v229, v228, s[28:29]
	v_max_f32_e32 v229, v228, v65
	v_cndmask_b32_e64 v228, v229, v228, s[26:27]
	v_max_f32_e32 v229, v228, v70
	v_cmp_gt_i32_e64 s[24:25], 32, v227
	v_cmp_gt_i32_e64 s[22:23], 33, v227
	s_nop 0
	v_cndmask_b32_e64 v228, v229, v228, s[24:25]
	v_max_f32_e32 v229, v228, v71
	v_cndmask_b32_e64 v228, v229, v228, s[22:23]
	v_max_f32_e32 v229, v228, v72
	v_cmp_gt_i32_e64 s[20:21], 34, v227
	v_cmp_gt_i32_e64 s[18:19], 35, v227
	s_nop 0
	v_cndmask_b32_e64 v228, v229, v228, s[20:21]
	v_max_f32_e32 v229, v228, v73
	v_cndmask_b32_e64 v228, v229, v228, s[18:19]
	v_max_f32_e32 v229, v228, v78
	v_cmp_gt_i32_e64 s[16:17], 48, v227
	v_cmp_gt_i32_e64 s[14:15], 49, v227
	s_nop 0
	v_cndmask_b32_e64 v228, v229, v228, s[16:17]
	v_max_f32_e32 v229, v228, v79
	v_cndmask_b32_e64 v228, v229, v228, s[14:15]
	v_max_f32_e32 v229, v228, v80
	v_cmp_gt_i32_e64 s[12:13], 50, v227
	v_max_f32_e32 v230, v81, v81
	v_cmp_gt_i32_e64 s[10:11], 51, v227
	v_cndmask_b32_e64 v228, v229, v228, s[12:13]
	v_max_f32_e32 v229, v228, v230
	v_cndmask_b32_e64 v227, v229, v228, s[10:11]
	v_add_f32_e32 v228, 0x41400000, v225
	v_cmp_gt_f32_e32 vcc, v227, v228
	s_cbranch_vccz .LBB0_937
	ds_bpermute_b32 v228, v173, v227
	v_max_f32_e32 v227, v227, v227
	s_waitcnt lgkmcnt(0)
	v_max_f32_e32 v228, v228, v228
	v_max_f32_e32 v227, v227, v228
	ds_bpermute_b32 v228, v222, v227
	s_waitcnt lgkmcnt(0)
	v_max3_f32 v227, v225, v227, v228
	v_sub_f32_e32 v225, v225, v227
	v_exp_f32_e32 v228, v225
	v_mov_b32_e32 v225, v227
	v_mul_f32_e32 v149, v149, v228
	v_pk_mul_f32 v[28:29], v[28:29], v[228:229] op_sel_hi:[1,0]
	v_pk_mul_f32 v[26:27], v[26:27], v[228:229] op_sel_hi:[1,0]
	v_pk_mul_f32 v[32:33], v[32:33], v[228:229] op_sel_hi:[1,0]
	v_pk_mul_f32 v[30:31], v[30:31], v[228:229] op_sel_hi:[1,0]
	v_pk_mul_f32 v[24:25], v[24:25], v[228:229] op_sel_hi:[1,0]
	v_pk_mul_f32 v[22:23], v[22:23], v[228:229] op_sel_hi:[1,0]
	v_pk_mul_f32 v[20:21], v[20:21], v[228:229] op_sel_hi:[1,0]
	v_pk_mul_f32 v[18:19], v[18:19], v[228:229] op_sel_hi:[1,0]

; __device__ __forceinline__ float shx(float v, int m) { return __shfl_xor(v, m); }
; template <class KB>
; __device__ __forceinline__ void sel_run(int nit, KB kbof, const half8 (&qf)[2][2], const unsigned char* kf, const unsigned char* vf, const int (&tqs)[2], int qq,
;                                         f32x4 (&o)[2][4], float (&m)[2], float (&l)[2], int g) {
;     ...
;         for (int s_ = 0; s_ < 2; ++s_)
;             if (need[s_]) {
;                 float p[4][4]; float mx = -1e30f;
;                 const int klim = selq[s_] ? tqs[s_] - kbA - 4 * g : -1;
; #pragma unroll
;                 for (int t = 0; t < 4; ++t)
; #pragma unroll
;                     for (int r = 0; r < 4; ++r) { if (16 * t + r <= klim) mx = fmaxf(mx, s[s_][t][r]); }
;                 if (__ballot(mx > m[s_] + RESC_THR) != 0ull) {
;                     mx = fmaxf(mx, shx(mx, 16)); mx = fmaxf(mx, shx(mx, 32));
;                     const float mn = fmaxf(m[s_], mx); const float corr = __builtin_amdgcn_exp2f(m[s_] - mn); m[s_] = mn;
;                     l[s_] = l[s_] * corr;
; #pragma unroll
;                     for (int dt = 0; dt < 4; ++dt) o[s_][dt] = o[s_][dt] * corr;
;                 }
.LBB0_938:
	s_andn2_b64 vcc, exec, s[2:3]
	s_cbranch_vccnz .LBB0_942
	s_cmp_le_u32 s100, s93
	s_cbranch_scc1 .Lsel_fast1
	v_lshrrev_b32_e64 v227, v214, s33
	v_and_b32_e32 v227, 1, v227
	v_add_u32_e32 v226, v226, v224
	v_cmp_eq_u32_e32 vcc, 1, v227
	v_max_f32_e32 v227, 0xf149f2ca, v50
	s_nop 0
	v_cndmask_b32_e32 v226, -1, v226, vcc
	v_cmp_gt_i32_e64 s[42:43], 0, v226
	v_cmp_gt_i32_e64 s[40:41], 1, v226
	s_nop 0
	v_cndmask_b32_e64 v227, v227, v172, s[42:43]
	v_max_f32_e32 v228, v227, v51
	v_cndmask_b32_e64 v227, v228, v227, s[40:41]
	v_max_f32_e32 v228, v227, v52
	v_cmp_gt_i32_e64 s[38:39], 2, v226
	v_cmp_gt_i32_e64 s[36:37], 3, v226
	v_cmp_gt_i32_e64 s[34:35], 16, v226
	v_cndmask_b32_e64 v227, v228, v227, s[38:39]
	v_max_f32_e32 v228, v227, v53
	v_cndmask_b32_e64 v227, v228, v227, s[36:37]
	v_max_f32_e32 v228, v227, v58
	v_cndmask_b32_e64 v227, v228, v227, s[34:35]
	v_max_f32_e32 v228, v227, v59
	v_cmp_gt_i32_e64 s[30:31], 17, v226
	v_cmp_gt_i32_e64 s[28:29], 18, v226
	s_nop 0
	v_cndmask_b32_e64 v227, v228, v227, s[30:31]
	v_max_f32_e32 v228, v227, v60
	v_cndmask_b32_e64 v227, v228, v227, s[28:29]
	v_max_f32_e32 v228, v227, v61
	v_cmp_gt_i32_e64 s[26:27], 19, v226
	v_cmp_gt_i32_e64 s[24:25], 32, v226
	s_nop 0
	v_cndmask_b32_e64 v227, v228, v227, s[26:27]
	v_max_f32_e32 v228, v227, v66
	v_cndmask_b32_e64 v227, v228, v227, s[24:25]
	v_max_f32_e32 v228, v227, v67
	v_cmp_gt_i32_e64 s[22:23], 33, v226
	v_cmp_gt_i32_e64 s[20:21], 34, v226
	s_nop 0
	v_cndmask_b32_e64 v227, v228, v227, s[22:23]
	v_max_f32_e32 v228, v227, v68
	v_cndmask_b32_e64 v227, v228, v227, s[20:21]
	v_max_f32_e32 v228, v227, v69
	v_cmp_gt_i32_e64 s[18:19], 35, v226
	v_cmp_gt_i32_e64 s[16:17], 48, v226
	s_nop 0
	v_cndmask_b32_e64 v227, v228, v227, s[18:19]
	v_max_f32_e32 v228, v227, v74
	v_cndmask_b32_e64 v227, v228, v227, s[16:17]
	v_max_f32_e32 v228, v227, v75
	v_cmp_gt_i32_e64 s[14:15], 49, v226
	v_cmp_gt_i32_e64 s[12:13], 50, v226
	s_nop 0
	v_cndmask_b32_e64 v227, v228, v227, s[14:15]
	v_max_f32_e32 v228, v227, v76
	v_cndmask_b32_e64 v227, v228, v227, s[12:13]
	v_max_f32_e32 v229, v77, v77
	v_max_f32_e32 v228, v227, v229
	v_cmp_gt_i32_e64 s[10:11], 51, v226
	s_nop 1
	v_cndmask_b32_e64 v226, v228, v227, s[10:11]
	v_add_f32_e32 v227, 0x41400000, v151
	v_cmp_gt_f32_e32 vcc, v226, v227
	s_cbranch_vccz .LBB0_941
	ds_bpermute_b32 v227, v173, v226
	v_max_f32_e32 v226, v226, v226
	s_waitcnt lgkmcnt(0)
	v_max_f32_e32 v227, v227, v227
	v_max_f32_e32 v226, v226, v227
	ds_bpermute_b32 v227, v222, v226
	s_waitcnt lgkmcnt(0)
	v_max3_f32 v227, v151, v226, v227
	v_sub_f32_e32 v151, v151, v227
	v_exp_f32_e32 v226, v151
	v_mov_b32_e32 v151, v227
	v_mul_f32_e32 v147, v147, v226
	v_pk_mul_f32 v[16:17], v[16:17], v[226:227] op_sel_hi:[1,0]
	v_pk_mul_f32 v[14:15], v[14:15], v[226:227] op_sel_hi:[1,0]
	v_pk_mul_f32 v[12:13], v[12:13], v[226:227] op_sel_hi:[1,0]
	v_pk_mul_f32 v[10:11], v[10:11], v[226:227] op_sel_hi:[1,0]
	v_pk_mul_f32 v[8:9], v[8:9], v[226:227] op_sel_hi:[1,0]
	v_pk_mul_f32 v[6:7], v[6:7], v[226:227] op_sel_hi:[1,0]
	v_pk_mul_f32 v[4:5], v[4:5], v[226:227] op_sel_hi:[1,0]
	v_pk_mul_f32 v[2:3], v[2:3], v[226:227] op_sel_hi:[1,0]

; #define MFMA16(a, b, c) __builtin_amdgcn_mfma_f32_16x16x32_f16((a), (b), (c), 0, 0, 0)
; __device__ __forceinline__ float shx(float v, int m) { return __shfl_xor(v, m); }
;     ...
;     for (int it = 0; it < nit; ++it) {
;         const int kbN = kbof((it + 1 < nit) ? it + 1 : it);
;         const int nbA = kbN >> 5, nbB = (nbA + 1 <= maxblk) ? nbA + 1 : maxblk;
;         const f32x4 z = {0.f, 0.f, 0.f, 0.f};
; #pragma unroll
;         for (int s_ = 0; s_ < NS; ++s_) {
;             f32x4 s[4];
; #pragma unroll
;             for (int t = 0; t < 4; ++t) { s[t] = MFMA16(ka[2 * t], qf[s_][0], z); s[t] = MFMA16(ka[2 * t + 1], qf[s_][1], s[t]); }
;             if (s_ == NS - 1) {
;                 const half_t* kpA = kf + (size_t)nbA * 2048; const half_t* kpB = kf + (size_t)nbB * 2048;
; #pragma unroll
;                 for (int i = 0; i < 4; ++i) { ka[i] = *(const half8*)(kpA + i * 512); ka[4 + i] = *(const half8*)(kpB + i * 512); }
;             }
;             if (MODE != 1) {
;                 float mx = -1e30f;
; #pragma unroll
;                 for (int t = 0; t < 4; ++t)
; #pragma unroll
;                     for (int r = 0; r < 4; ++r) { if (valid(s_, kbA + 16 * t + 4 * g + r)) mx = fmaxf(mx, s[t][r]); }
;                 if (__ballot(mx > m[s_] + RESC_THR) != 0ull) {
;                     mx = fmaxf(mx, shx(mx, 16)); mx = fmaxf(mx, shx(mx, 32));
;                     const float mn = fmaxf(m[s_], mx); const float corr = __builtin_amdgcn_exp2f(m[s_] - mn); m[s_] = mn; l[s_] = l[s_] * corr;
;                     if (PV) {
; #pragma unroll
;                         for (int dt = 0; dt < 4; ++dt) o[s_][dt] = o[s_][dt] * corr;
;                     }
;                 }
;             }
; __device__ __forceinline__ void a_unit(const ACtx& X, int b, int t0, float* ldsw, int lane) {
;     ...
;         auto valid = [&](int, int key) { return key <= tq && tq - key <= 511; };
.LBB0_947:
	global_load_dwordx4 v[106:109], v[82:83], off
	global_load_dwordx4 v[98:101], v[82:83], off offset:1024
	global_load_dwordx4 v[90:93], v[82:83], off offset:2048
	s_nop 0
	global_load_dwordx4 v[82:85], v[82:83], off offset:3072
	s_nop 0
	global_load_dwordx4 v[110:113], v[86:87], off
	global_load_dwordx4 v[102:105], v[86:87], off offset:1024
	global_load_dwordx4 v[94:97], v[86:87], off offset:2048
	s_nop 0
	global_load_dwordx4 v[86:89], v[86:87], off offset:3072
	s_waitcnt vmcnt(8) lgkmcnt(0)
	v_mfma_f32_16x16x32_f16 v[114:117], v[70:73], v[34:37], 0
	v_add_u32_e32 v158, s49, v166
	v_cmp_le_i32_e32 vcc, v158, v149
	v_cmp_gt_i32_e64 s[10:11], v158, v162
	v_mfma_f32_16x16x32_f16 v[126:129], v[78:81], v[38:41], v[114:117]
	s_and_b64 s[10:11], vcc, s[10:11]
	v_sub_u32_e32 v160, v158, v149
	s_movk_i32 s2, 0xfdff
	v_cmp_lt_i32_e32 vcc, v158, v149
	v_cmp_lt_i32_e64 s[12:13], s2, v160
	s_nop 2
	v_max_f32_e32 v159, 0xf149f2ca, v126
	v_cndmask_b32_e64 v159, v172, v159, s[10:11]
	v_mfma_f32_16x16x32_f16 v[114:117], v[74:77], v[34:37], 0
	s_and_b64 s[12:13], vcc, s[12:13]
	v_max_f32_e32 v160, v159, v127
	v_cndmask_b32_e64 v159, v159, v160, s[12:13]
	v_add_u32_e32 v160, 2, v158
	v_cmp_le_i32_e32 vcc, v160, v149
	v_cmp_gt_i32_e64 s[14:15], v160, v162
	s_and_b64 s[14:15], vcc, s[14:15]
	v_max_f32_e32 v160, v159, v128
	v_mfma_f32_16x16x32_f16 v[122:125], v[66:69], v[38:41], v[114:117]
	v_cndmask_b32_e64 v159, v159, v160, s[14:15]
	v_add_u32_e32 v160, 3, v158
	v_cmp_le_i32_e32 vcc, v160, v149
	v_cmp_gt_i32_e64 s[16:17], v160, v162
	s_and_b64 s[18:19], vcc, s[16:17]
	v_max_f32_e32 v160, v159, v129
	v_cndmask_b32_e64 v159, v159, v160, s[18:19]
	v_add_u32_e32 v160, 16, v158
	v_cmp_le_i32_e32 vcc, v160, v149
	v_cmp_gt_i32_e64 s[16:17], v160, v162
	s_and_b64 s[16:17], vcc, s[16:17]
	v_max_f32_e32 v160, v159, v122
	v_cndmask_b32_e64 v159, v159, v160, s[16:17]
	v_add_u32_e32 v160, 17, v158
	v_cmp_le_i32_e32 vcc, v160, v149
	v_cmp_gt_i32_e64 s[20:21], v160, v162
	v_mfma_f32_16x16x32_f16 v[114:117], v[62:65], v[34:37], 0
	s_and_b64 s[20:21], vcc, s[20:21]
	v_max_f32_e32 v160, v159, v123
	v_cndmask_b32_e64 v159, v159, v160, s[20:21]
	v_add_u32_e32 v160, 18, v158
	v_cmp_le_i32_e32 vcc, v160, v149
	v_cmp_gt_i32_e64 s[22:23], v160, v162
	s_and_b64 s[22:23], vcc, s[22:23]
	v_max_f32_e32 v160, v159, v124
	v_mfma_f32_16x16x32_f16 v[118:121], v[58:61], v[38:41], v[114:117]
	v_cndmask_b32_e64 v159, v159, v160, s[22:23]
	v_add_u32_e32 v160, 19, v158
	v_cmp_le_i32_e32 vcc, v160, v149
	v_cmp_gt_i32_e64 s[24:25], v160, v162
	s_and_b64 s[26:27], vcc, s[24:25]
	v_max_f32_e32 v160, v159, v125
	v_cndmask_b32_e64 v159, v159, v160, s[26:27]
	v_add_u32_e32 v160, 32, v158
	v_cmp_le_i32_e32 vcc, v160, v149
	v_cmp_gt_i32_e64 s[24:25], v160, v162
	s_and_b64 s[24:25], vcc, s[24:25]
	v_max_f32_e32 v160, v159, v118
	v_cndmask_b32_e64 v159, v159, v160, s[24:25]
	v_add_u32_e32 v160, 33, v158
	v_cmp_le_i32_e32 vcc, v160, v149
	v_cmp_gt_i32_e64 s[28:29], v160, v162
	v_mfma_f32_16x16x32_f16 v[114:117], v[54:57], v[34:37], 0
	s_and_b64 s[28:29], vcc, s[28:29]
	v_max_f32_e32 v160, v159, v119
	v_cndmask_b32_e64 v159, v159, v160, s[28:29]
	v_add_u32_e32 v160, 34, v158
	v_cmp_le_i32_e32 vcc, v160, v149
	v_cmp_gt_i32_e64 s[30:31], v160, v162
	s_and_b64 s[30:31], vcc, s[30:31]
	v_max_f32_e32 v160, v159, v120
	v_mfma_f32_16x16x32_f16 v[114:117], v[50:53], v[38:41], v[114:117]
	v_cndmask_b32_e64 v159, v159, v160, s[30:31]
	v_add_u32_e32 v160, 35, v158
	v_cmp_le_i32_e32 vcc, v160, v149
	v_cmp_gt_i32_e64 s[34:35], v160, v162
	s_and_b64 s[36:37], vcc, s[34:35]
	v_max_f32_e32 v160, v159, v121
	v_cndmask_b32_e64 v159, v159, v160, s[36:37]
	v_add_u32_e32 v160, 48, v158
	v_cmp_le_i32_e32 vcc, v160, v149
	v_cmp_gt_i32_e64 s[34:35], v160, v162
	s_and_b64 s[34:35], vcc, s[34:35]
	v_max_f32_e32 v160, v159, v114
	v_cndmask_b32_e64 v159, v159, v160, s[34:35]
	v_add_u32_e32 v160, 49, v158
	v_cmp_le_i32_e32 vcc, v160, v149
	v_cmp_gt_i32_e64 s[38:39], v160, v162
	s_and_b64 s[38:39], vcc, s[38:39]
	v_max_f32_e32 v160, v159, v115
	v_cndmask_b32_e64 v159, v159, v160, s[38:39]
	v_add_u32_e32 v160, 50, v158
	v_cmp_le_i32_e32 vcc, v160, v149
	v_cmp_gt_i32_e64 s[40:41], v160, v162
	v_max_f32_e32 v161, v116, v116
	s_and_b64 s[40:41], vcc, s[40:41]
	v_max_f32_e32 v160, v159, v161
	v_cndmask_b32_e64 v159, v159, v160, s[40:41]
	v_add_u32_e32 v158, 51, v158
	v_cmp_le_i32_e32 vcc, v158, v149
	v_cmp_gt_i32_e64 s[42:43], v158, v162
	v_max_f32_e32 v160, v117, v117
	s_and_b64 s[42:43], vcc, s[42:43]
	v_max_f32_e32 v158, v159, v160
	v_cndmask_b32_e64 v158, v159, v158, s[42:43]
	v_add_f32_e32 v159, 0x41400000, v168
	v_cmp_gt_f32_e32 vcc, v158, v159
	s_cbranch_vccz .LBB0_949
	ds_bpermute_b32 v159, v173, v158
	v_max_f32_e32 v158, v158, v158
	s_waitcnt lgkmcnt(0)
	v_max_f32_e32 v159, v159, v159
	v_max_f32_e32 v158, v158, v159
	ds_bpermute_b32 v159, v222, v158
	s_waitcnt lgkmcnt(0)
	v_max3_f32 v159, v168, v158, v159
	v_sub_f32_e32 v158, v168, v159
	v_exp_f32_e32 v158, v158
	v_mov_b32_e32 v168, v159
	v_mul_f32_e32 v151, v151, v158
	v_pk_mul_f32 v[32:33], v[32:33], v[158:159] op_sel_hi:[1,0]
	v_pk_mul_f32 v[30:31], v[30:31], v[158:159] op_sel_hi:[1,0]
	v_pk_mul_f32 v[28:29], v[28:29], v[158:159] op_sel_hi:[1,0]
	v_pk_mul_f32 v[26:27], v[26:27], v[158:159] op_sel_hi:[1,0]
	v_pk_mul_f32 v[24:25], v[24:25], v[158:159] op_sel_hi:[1,0]
	v_pk_mul_f32 v[22:23], v[22:23], v[158:159] op_sel_hi:[1,0]
	v_pk_mul_f32 v[20:21], v[20:21], v[158:159] op_sel_hi:[1,0]
	v_pk_mul_f32 v[18:19], v[18:19], v[158:159] op_sel_hi:[1,0]
; #define MFMA16(a, b, c) __builtin_amdgcn_mfma_f32_16x16x32_f16((a), (b), (c), 0, 0, 0)
; __device__ __forceinline__ float shx(float v, int m) { return __shfl_xor(v, m); }
;     ...
;             for (int t = 0; t < 4; ++t) { s[t] = MFMA16(ka[2 * t], qf[s_][0], z); s[t] = MFMA16(ka[2 * t + 1], qf[s_][1], s[t]); }
;             if (s_ == NS - 1) {
;                 const half_t* kpA = kf + (size_t)nbA * 2048; const half_t* kpB = kf + (size_t)nbB * 2048;
; #pragma unroll
;                 for (int i = 0; i < 4; ++i) { ka[i] = *(const half8*)(kpA + i * 512); ka[4 + i] = *(const half8*)(kpB + i * 512); }
;             }
;             if (MODE != 1) {
;                 float mx = -1e30f;
; #pragma unroll
;                 for (int t = 0; t < 4; ++t)
; #pragma unroll
;                     for (int r = 0; r < 4; ++r) { if (valid(s_, kbA + 16 * t + 4 * g + r)) mx = fmaxf(mx, s[t][r]); }
;                 if (__ballot(mx > m[s_] + RESC_THR) != 0ull) {
;                     mx = fmaxf(mx, shx(mx, 16)); mx = fmaxf(mx, shx(mx, 32));
;                     const float mn = fmaxf(m[s_], mx); const float corr = __builtin_amdgcn_exp2f(m[s_] - mn); m[s_] = mn; l[s_] = l[s_] * corr;
;                     if (PV) {
; #pragma unroll
;                         for (int dt = 0; dt < 4; ++dt) o[s_][dt] = o[s_][dt] * corr;
;                     }
;                 }
;             }
;             float p[4][4]; float ps = 0.f;
; #pragma unroll
;             for (int t = 0; t < 4; ++t)
; #pragma unroll
;                 for (int r = 0; r < 4; ++r) { p[t][r] = valid(s_, kbA + 16 * t + 4 * g + r) ? __builtin_amdgcn_exp2f(s[t][r] - m[s_]) : 0.f; if (MODE == 1) p[t][r] *= l[s_]; ps += p[t][r]; }
;             if (MODE != 1) l[s_] = l[s_] + ps;
;             if (PV) {
;                 const half8 pfA = {(half_t)p[0][0], (half_t)p[0][1], (half_t)p[0][2], (half_t)p[0][3], (half_t)p[1][0], (half_t)p[1][1], (half_t)p[1][2], (half_t)p[1][3]};
;                 const half8 pfB = {(half_t)p[2][0], (half_t)p[2][1], (half_t)p[2][2], (half_t)p[2][3], (half_t)p[3][0], (half_t)p[3][1], (half_t)p[3][2], (half_t)p[3][3]};
; #pragma unroll
;                 for (int dt = 0; dt < 4; ++dt) { o[s_][dt] = MFMA16(va[dt], pfA, o[s_][dt]); o[s_][dt] = MFMA16(va[4 + dt], pfB, o[s_][dt]); }
;             }
.LBB0_949:
	v_sub_f32_e32 v126, v126, v168
	v_sub_f32_e32 v122, v122, v168
	v_exp_f32_e32 v126, v126
	v_exp_f32_e32 v122, v122
	v_sub_f32_e32 v114, v114, v168
	v_exp_f32_e32 v114, v114
	v_sub_f32_e32 v118, v118, v168
	v_cndmask_b32_e64 v169, 0, v126, s[10:11]
	v_sub_f32_e32 v126, v127, v168
	v_cndmask_b32_e64 v183, 0, v122, s[16:17]
	v_sub_f32_e32 v122, v123, v168
	v_exp_f32_e32 v118, v118
	v_exp_f32_e32 v126, v126
	v_exp_f32_e32 v122, v122
	v_cndmask_b32_e64 v224, 0, v114, s[34:35]
	v_sub_f32_e32 v114, v115, v168
	v_exp_f32_e32 v114, v114
	v_cndmask_b32_e64 v187, 0, v118, s[24:25]
	v_sub_f32_e32 v118, v119, v168
	v_cndmask_b32_e64 v180, 0, v126, s[12:13]
	v_sub_f32_e32 v126, v128, v168
	v_cndmask_b32_e64 v184, 0, v122, s[20:21]
	v_sub_f32_e32 v122, v124, v168
	v_exp_f32_e32 v118, v118
	v_exp_f32_e32 v126, v126
	v_exp_f32_e32 v122, v122
	v_cndmask_b32_e64 v225, 0, v114, s[38:39]
	v_sub_f32_e32 v114, v116, v168
	v_exp_f32_e32 v114, v114
	v_cndmask_b32_e64 v188, 0, v118, s[28:29]
	v_sub_f32_e32 v118, v120, v168
	v_cndmask_b32_e64 v181, 0, v126, s[14:15]
	v_sub_f32_e32 v126, v129, v168
	v_cndmask_b32_e64 v185, 0, v122, s[22:23]
	v_sub_f32_e32 v122, v125, v168
	v_exp_f32_e32 v118, v118
	v_exp_f32_e32 v126, v126
	v_exp_f32_e32 v122, v122
	v_cndmask_b32_e64 v226, 0, v114, s[40:41]
	v_sub_f32_e32 v114, v117, v168
	v_exp_f32_e32 v114, v114
	s_add_i32 s50, s48, 1
	v_cndmask_b32_e64 v189, 0, v118, s[30:31]
	v_sub_f32_e32 v118, v121, v168
	s_cmp_lt_i32 s48, s46
	v_cndmask_b32_e64 v182, 0, v126, s[18:19]
	v_cndmask_b32_e64 v186, 0, v122, s[26:27]
	v_exp_f32_e32 v118, v118
	s_cselect_b32 s2, s50, s48
	v_cndmask_b32_e64 v227, 0, v114, s[42:43]
	v_cvt_pk_f16_f32 v117, v185, v186
	v_cvt_pk_f16_f32 v116, v183, v184
	v_cvt_pk_f16_f32 v115, v181, v182
	v_cvt_pk_f16_f32 v114, v169, v180
	s_lshl_b32 s2, s2, 6
	v_mfma_f32_16x16x32_f16 v[70:73], v[70:73], v[42:45], 0
	s_add_i32 s49, s2, s47
	s_ashr_i32 s2, s49, 5
	v_cndmask_b32_e64 v223, 0, v118, s[36:37]
	s_waitcnt vmcnt(0)
	v_mfma_f32_16x16x32_f16 v[30:33], v[106:109], v[114:117], v[30:33]
	s_min_i32 s44, s2, 0x1fe
	v_cvt_pk_f16_f32 v121, v226, v227
	v_cvt_pk_f16_f32 v120, v224, v225
	v_mfma_f32_16x16x32_f16 v[26:29], v[98:101], v[114:117], v[26:29]
	v_cvt_pk_f16_f32 v119, v189, v223
	v_cvt_pk_f16_f32 v118, v187, v188
	s_ashr_i32 s3, s2, 31
	v_mfma_f32_16x16x32_f16 v[22:25], v[90:93], v[114:117], v[22:25]
	s_ashr_i32 s45, s44, 31
	s_lshl_b64 s[2:3], s[2:3], 12
	s_lshl_b64 s[44:45], s[44:45], 12
	v_mfma_f32_16x16x32_f16 v[18:21], v[82:85], v[114:117], v[18:21]
	s_add_u32 s44, s44, 0x1000
	v_lshl_add_u64 v[158:159], v[154:155], 0, s[2:3]
	s_addc_u32 s45, s45, 0
	v_mfma_f32_16x16x32_f16 v[30:33], v[110:113], v[118:121], v[30:33]
	v_lshl_add_u64 v[160:161], v[154:155], 0, s[44:45]
	v_mfma_f32_16x16x32_f16 v[26:29], v[102:105], v[118:121], v[26:29]
	v_mfma_f32_16x16x32_f16 v[22:25], v[94:97], v[118:121], v[22:25]
	v_mfma_f32_16x16x32_f16 v[18:21], v[86:89], v[118:121], v[18:21]
	v_mfma_f32_16x16x32_f16 v[118:121], v[78:81], v[46:49], v[70:73]
	v_mfma_f32_16x16x32_f16 v[70:73], v[74:77], v[42:45], 0
	v_mfma_f32_16x16x32_f16 v[62:65], v[62:65], v[42:45], 0
	v_mfma_f32_16x16x32_f16 v[54:57], v[54:57], v[42:45], 0
	v_mfma_f32_16x16x32_f16 v[114:117], v[66:69], v[46:49], v[70:73]
	v_mfma_f32_16x16x32_f16 v[122:125], v[58:61], v[46:49], v[62:65]
	v_mfma_f32_16x16x32_f16 v[126:129], v[50:53], v[46:49], v[54:57]
	s_nop 2
	global_load_dwordx4 v[70:73], v[158:159], off
	global_load_dwordx4 v[62:65], v[160:161], off
	global_load_dwordx4 v[78:81], v[158:159], off offset:1024
	global_load_dwordx4 v[58:61], v[160:161], off offset:1024
	global_load_dwordx4 v[74:77], v[158:159], off offset:2048
	global_load_dwordx4 v[54:57], v[160:161], off offset:2048
	global_load_dwordx4 v[66:69], v[158:159], off offset:3072
	global_load_dwordx4 v[50:53], v[160:161], off offset:3072
	v_max_f32_e32 v158, 0xf149f2ca, v118
	v_cndmask_b32_e64 v158, v172, v158, s[10:11]
	v_max_f32_e32 v159, v158, v119
	v_cndmask_b32_e64 v158, v158, v159, s[12:13]
	v_max_f32_e32 v159, v158, v120
	v_cndmask_b32_e64 v158, v158, v159, s[14:15]
	v_max_f32_e32 v159, v158, v121
	v_cndmask_b32_e64 v158, v158, v159, s[18:19]
	v_max_f32_e32 v159, v158, v114
	v_cndmask_b32_e64 v158, v158, v159, s[16:17]
	v_max_f32_e32 v159, v158, v115
	v_cndmask_b32_e64 v158, v158, v159, s[20:21]
	v_max_f32_e32 v159, v158, v116
	v_cndmask_b32_e64 v158, v158, v159, s[22:23]
	v_max_f32_e32 v159, v158, v117
	v_cndmask_b32_e64 v158, v158, v159, s[26:27]
	v_max_f32_e32 v159, v158, v122
	v_cndmask_b32_e64 v158, v158, v159, s[24:25]
	v_max_f32_e32 v159, v158, v123
	v_cndmask_b32_e64 v158, v158, v159, s[28:29]
	v_max_f32_e32 v159, v158, v124
	v_cndmask_b32_e64 v158, v158, v159, s[30:31]
	v_max_f32_e32 v159, v158, v125
	v_cndmask_b32_e64 v158, v158, v159, s[36:37]
	v_max_f32_e32 v159, v158, v126
	v_cndmask_b32_e64 v158, v158, v159, s[34:35]
	v_max_f32_e32 v159, v158, v127
	v_cndmask_b32_e64 v158, v158, v159, s[38:39]
	v_max_f32_e32 v159, v158, v128
	v_cndmask_b32_e64 v158, v158, v159, s[40:41]
	v_max_f32_e32 v160, v129, v129
	v_max_f32_e32 v159, v158, v160
	v_cndmask_b32_e64 v158, v158, v159, s[42:43]
	v_add_f32_e32 v159, 0x41400000, v163
	v_cmp_gt_f32_e32 vcc, v158, v159
	s_cbranch_vccz .LBB0_951
	ds_bpermute_b32 v159, v173, v158
	v_max_f32_e32 v158, v158, v158
	s_waitcnt lgkmcnt(0)
	v_max_f32_e32 v159, v159, v159
	v_max_f32_e32 v158, v158, v159
	ds_bpermute_b32 v159, v222, v158
	s_waitcnt lgkmcnt(0)
	v_max3_f32 v159, v163, v158, v159
	v_sub_f32_e32 v158, v163, v159
	v_exp_f32_e32 v158, v158
	v_mov_b32_e32 v163, v159
	v_mul_f32_e32 v147, v147, v158
	v_pk_mul_f32 v[16:17], v[16:17], v[158:159] op_sel_hi:[1,0]
	v_pk_mul_f32 v[14:15], v[14:15], v[158:159] op_sel_hi:[1,0]
	v_pk_mul_f32 v[12:13], v[12:13], v[158:159] op_sel_hi:[1,0]
	v_pk_mul_f32 v[10:11], v[10:11], v[158:159] op_sel_hi:[1,0]
	v_pk_mul_f32 v[8:9], v[8:9], v[158:159] op_sel_hi:[1,0]
	v_pk_mul_f32 v[6:7], v[6:7], v[158:159] op_sel_hi:[1,0]
	v_pk_mul_f32 v[4:5], v[4:5], v[158:159] op_sel_hi:[1,0]
	v_pk_mul_f32 v[2:3], v[2:3], v[158:159] op_sel_hi:[1,0]

; #define MFMA16(a, b, c) __builtin_amdgcn_mfma_f32_16x16x32_f16((a), (b), (c), 0, 0, 0)
; __device__ __forceinline__ float shx(float v, int m) { return __shfl_xor(v, m); }
;     ...
;         const int kbN = kbof((it + 1 < nit) ? it + 1 : it);
;         const int nbA = kbN >> 5, nbB = (nbA + 1 <= maxblk) ? nbA + 1 : maxblk;
;         const f32x4 z = {0.f, 0.f, 0.f, 0.f};
; #pragma unroll
;         for (int s_ = 0; s_ < NS; ++s_) {
;             f32x4 s[4];
; #pragma unroll
;             for (int t = 0; t < 4; ++t) { s[t] = MFMA16(ka[2 * t], qf[s_][0], z); s[t] = MFMA16(ka[2 * t + 1], qf[s_][1], s[t]); }
;             if (s_ == NS - 1) {
;                 const half_t* kpA = kf + (size_t)nbA * 2048; const half_t* kpB = kf + (size_t)nbB * 2048;
; #pragma unroll
;                 for (int i = 0; i < 4; ++i) { ka[i] = *(const half8*)(kpA + i * 512); ka[4 + i] = *(const half8*)(kpB + i * 512); }
;             }
;             if (MODE != 1) {
;                 float mx = -1e30f;
; #pragma unroll
;                 for (int t = 0; t < 4; ++t)
; #pragma unroll
;                     for (int r = 0; r < 4; ++r) { if (valid(s_, kbA + 16 * t + 4 * g + r)) mx = fmaxf(mx, s[t][r]); }
;                 if (__ballot(mx > m[s_] + RESC_THR) != 0ull) {
;                     mx = fmaxf(mx, shx(mx, 16)); mx = fmaxf(mx, shx(mx, 32));
;                     const float mn = fmaxf(m[s_], mx); const float corr = __builtin_amdgcn_exp2f(m[s_] - mn); m[s_] = mn; l[s_] = l[s_] * corr;
;                     if (PV) {
; #pragma unroll
;                         for (int dt = 0; dt < 4; ++dt) o[s_][dt] = o[s_][dt] * corr;
;                     }
;                 }
;             }
; __device__ __forceinline__ void b_unit(const ACtx& X, int b, int h6, int fb, int lane) {
;     ...
;     auto valid = [&](int s_, int kf) { return kf <= iqs[s_] && iqs[s_] - kf <= 128; };
.LBB0_959:
	s_waitcnt vmcnt(0) lgkmcnt(0)
	v_mfma_f32_16x16x32_f16 v[86:89], v[78:81], v[34:37], 0
	flat_load_dwordx4 v[110:113], v[84:85]
	flat_load_dwordx4 v[102:105], v[84:85] offset:1024
	v_add_u32_e32 v150, s54, v166
	v_cmp_ge_i32_e32 vcc, v147, v150
	v_mfma_f32_16x16x32_f16 v[122:125], v[74:77], v[38:41], v[86:89]
	flat_load_dwordx4 v[94:97], v[84:85] offset:2048
	s_nop 1
	flat_load_dwordx4 v[86:89], v[84:85] offset:3072
	flat_load_dwordx4 v[106:109], v[82:83]
	flat_load_dwordx4 v[98:101], v[82:83] offset:1024
	flat_load_dwordx4 v[90:93], v[82:83] offset:2048
	s_nop 0
	flat_load_dwordx4 v[82:85], v[82:83] offset:3072
	v_cmp_gt_i32_e64 s[6:7], v150, v133
	v_mfma_f32_16x16x32_f16 v[114:117], v[70:73], v[34:37], 0
	s_and_b64 s[6:7], vcc, s[6:7]
	v_cmp_gt_i32_e32 vcc, v147, v150
	v_cmp_ge_i32_e64 s[8:9], v150, v133
	v_mfma_f32_16x16x32_f16 v[126:129], v[58:61], v[38:41], v[114:117]
	s_and_b64 s[8:9], vcc, s[8:9]
	v_add_u32_e32 v151, 2, v150
	v_cmp_le_i32_e32 vcc, v151, v147
	s_nop 0
	v_max_f32_e32 v118, 0xf149f2ca, v122
	v_mfma_f32_16x16x32_f16 v[114:117], v[66:69], v[34:37], 0
	v_cndmask_b32_e64 v144, v172, v118, s[6:7]
	v_cmp_gt_i32_e64 s[10:11], v151, v133
	s_and_b64 s[12:13], vcc, s[10:11]
	v_mfma_f32_16x16x32_f16 v[118:121], v[62:65], v[38:41], v[114:117]
	v_add_u32_e32 v152, 3, v150
	v_cmp_le_i32_e32 vcc, v152, v147
	v_cmp_gt_i32_e64 s[10:11], v152, v133
	s_nop 0
	v_max_f32_e32 v145, v144, v123
	v_cndmask_b32_e64 v144, v144, v145, s[8:9]
	v_max_f32_e32 v145, v144, v124
	v_cndmask_b32_e64 v144, v144, v145, s[12:13]
	v_max_f32_e32 v145, v144, v125
	s_and_b64 s[14:15], vcc, s[10:11]
	v_add_u32_e32 v155, 16, v150
	v_cndmask_b32_e64 v144, v144, v145, s[14:15]
	v_cmp_le_i32_e32 vcc, v155, v147
	v_cmp_gt_i32_e64 s[10:11], v155, v133
	v_max_f32_e32 v145, v144, v126
	s_and_b64 s[10:11], vcc, s[10:11]
	v_cndmask_b32_e64 v144, v144, v145, s[10:11]
	v_add_u32_e32 v153, 17, v150
	v_cmp_le_i32_e32 vcc, v153, v147
	v_cmp_gt_i32_e64 s[16:17], v153, v133
	v_max_f32_e32 v145, v144, v127
	s_and_b64 s[16:17], vcc, s[16:17]
	v_cndmask_b32_e64 v144, v144, v145, s[16:17]
	v_add_u32_e32 v154, 18, v150
	v_cmp_le_i32_e32 vcc, v154, v147
	v_cmp_gt_i32_e64 s[18:19], v154, v133
	v_max_f32_e32 v145, v144, v128
	s_and_b64 s[18:19], vcc, s[18:19]
	v_cndmask_b32_e64 v144, v144, v145, s[18:19]
	v_add_u32_e32 v156, 19, v150
	v_cmp_le_i32_e32 vcc, v156, v147
	v_cmp_gt_i32_e64 s[20:21], v156, v133
	v_max_f32_e32 v145, v144, v129
	s_and_b64 s[22:23], vcc, s[20:21]
	v_cndmask_b32_e64 v144, v144, v145, s[22:23]
	v_add_u32_e32 v157, 32, v150
	v_cmp_le_i32_e32 vcc, v157, v147
	v_cmp_gt_i32_e64 s[20:21], v157, v133
	v_max_f32_e32 v145, v144, v118
	s_and_b64 s[20:21], vcc, s[20:21]
	v_cndmask_b32_e64 v144, v144, v145, s[20:21]
	v_add_u32_e32 v158, 33, v150
	v_cmp_le_i32_e32 vcc, v158, v147
	v_cmp_gt_i32_e64 s[24:25], v158, v133
	v_mfma_f32_16x16x32_f16 v[114:117], v[54:57], v[34:37], 0
	v_max_f32_e32 v145, v144, v119
	s_and_b64 s[24:25], vcc, s[24:25]
	v_cndmask_b32_e64 v144, v144, v145, s[24:25]
	v_add_u32_e32 v159, 34, v150
	v_cmp_le_i32_e32 vcc, v159, v147
	v_cmp_gt_i32_e64 s[26:27], v159, v133
	v_max_f32_e32 v145, v144, v120
	s_and_b64 s[26:27], vcc, s[26:27]
	v_mfma_f32_16x16x32_f16 v[114:117], v[50:53], v[38:41], v[114:117]
	v_cndmask_b32_e64 v144, v144, v145, s[26:27]
	v_add_u32_e32 v160, 35, v150
	v_cmp_le_i32_e32 vcc, v160, v147
	v_cmp_gt_i32_e64 s[28:29], v160, v133
	v_max_f32_e32 v145, v144, v121
	s_and_b64 s[30:31], vcc, s[28:29]
	v_cndmask_b32_e64 v144, v144, v145, s[30:31]
	v_add_u32_e32 v161, 48, v150
	v_cmp_le_i32_e32 vcc, v161, v147
	v_cmp_gt_i32_e64 s[28:29], v161, v133
	v_max_f32_e32 v145, v144, v114
	s_and_b64 s[28:29], vcc, s[28:29]
	v_cndmask_b32_e64 v144, v144, v145, s[28:29]
	v_add_u32_e32 v162, 49, v150
	v_cmp_le_i32_e32 vcc, v162, v147
	v_cmp_gt_i32_e64 s[34:35], v162, v133
	v_max_f32_e32 v145, v144, v115
	s_and_b64 s[34:35], vcc, s[34:35]
	v_cndmask_b32_e64 v144, v144, v145, s[34:35]
	v_add_u32_e32 v163, 50, v150
	v_cmp_le_i32_e32 vcc, v163, v147
	v_cmp_gt_i32_e64 s[36:37], v163, v133
	v_max_f32_e32 v145, v144, v116
	s_and_b64 s[36:37], vcc, s[36:37]
	v_cndmask_b32_e64 v144, v144, v145, s[36:37]
	v_add_u32_e32 v167, 51, v150
	v_cmp_le_i32_e32 vcc, v167, v147
	v_cmp_gt_i32_e64 s[38:39], v167, v133
	v_max_f32_e32 v168, v117, v117
	v_max_f32_e32 v145, v144, v168
	s_and_b64 s[38:39], vcc, s[38:39]
	v_cndmask_b32_e64 v144, v144, v145, s[38:39]
	v_add_f32_e32 v145, 0x41400000, v136
	v_cmp_gt_f32_e32 vcc, v144, v145
	s_cbranch_vccz .LBB0_961
	ds_bpermute_b32 v145, v139, v144
	v_max_f32_e32 v144, v144, v144
	s_waitcnt lgkmcnt(0)
	v_max_f32_e32 v145, v145, v145
	v_max_f32_e32 v144, v144, v145
	ds_bpermute_b32 v145, v146, v144
	s_waitcnt lgkmcnt(0)
	v_max3_f32 v144, v136, v144, v145
	v_sub_f32_e32 v136, v136, v144
	v_exp_f32_e32 v136, v136
	v_mov_b32_e32 v145, v137
	v_mul_f32_e32 v138, v138, v136
	v_pk_mul_f32 v[32:33], v[32:33], v[136:137] op_sel_hi:[1,0]
	v_pk_mul_f32 v[30:31], v[30:31], v[136:137] op_sel_hi:[1,0]
	v_pk_mul_f32 v[28:29], v[28:29], v[136:137] op_sel_hi:[1,0]
	v_pk_mul_f32 v[26:27], v[26:27], v[136:137] op_sel_hi:[1,0]
	v_pk_mul_f32 v[24:25], v[24:25], v[136:137] op_sel_hi:[1,0]
	v_pk_mul_f32 v[22:23], v[22:23], v[136:137] op_sel_hi:[1,0]
	v_pk_mul_f32 v[20:21], v[20:21], v[136:137] op_sel_hi:[1,0]
	v_pk_mul_f32 v[18:19], v[18:19], v[136:137] op_sel_hi:[1,0]
	v_mov_b32_e32 v136, v144
	s_branch .LBB0_962

; #define MFMA16(a, b, c) __builtin_amdgcn_mfma_f32_16x16x32_f16((a), (b), (c), 0, 0, 0)
;     ...
;             float p[4][4]; float ps = 0.f;
; #pragma unroll
;             for (int t = 0; t < 4; ++t)
; #pragma unroll
;                 for (int r = 0; r < 4; ++r) { p[t][r] = valid(s_, kbA + 16 * t + 4 * g + r) ? __builtin_amdgcn_exp2f(s[t][r] - m[s_]) : 0.f; if (MODE == 1) p[t][r] *= l[s_]; ps += p[t][r]; }
;             if (MODE != 1) l[s_] = l[s_] + ps;
;             if (PV) {
;                 const half8 pfA = {(half_t)p[0][0], (half_t)p[0][1], (half_t)p[0][2], (half_t)p[0][3], (half_t)p[1][0], (half_t)p[1][1], (half_t)p[1][2], (half_t)p[1][3]};
;                 const half8 pfB = {(half_t)p[2][0], (half_t)p[2][1], (half_t)p[2][2], (half_t)p[2][3], (half_t)p[3][0], (half_t)p[3][1], (half_t)p[3][2], (half_t)p[3][3]};
; #pragma unroll
;                 for (int dt = 0; dt < 4; ++dt) { o[s_][dt] = MFMA16(va[dt], pfA, o[s_][dt]); o[s_][dt] = MFMA16(va[4 + dt], pfB, o[s_][dt]); }
.LBB0_962:
	v_sub_f32_e32 v122, v122, v136
	v_exp_f32_e32 v122, v122
	v_sub_f32_e32 v123, v123, v136
	v_sub_f32_e32 v126, v126, v136
	v_sub_f32_e32 v127, v127, v136
	v_sub_f32_e32 v128, v128, v136
	v_sub_f32_e32 v129, v129, v136
	v_exp_f32_e32 v123, v123
	v_sub_f32_e32 v124, v124, v136
	v_exp_f32_e32 v126, v126
	v_exp_f32_e32 v127, v127
	v_exp_f32_e32 v128, v128
	v_exp_f32_e32 v129, v129
	v_mfma_f32_16x16x32_f16 v[78:81], v[78:81], v[42:45], 0
	v_exp_f32_e32 v124, v124
	v_sub_f32_e32 v125, v125, v136
	v_exp_f32_e32 v125, v125
	v_cndmask_b32_e64 v122, 0, v122, s[6:7]
	v_cndmask_b32_e64 v123, 0, v123, s[8:9]
	v_cndmask_b32_e64 v173, 0, v126, s[10:11]
	v_cndmask_b32_e64 v180, 0, v127, s[16:17]
	v_cndmask_b32_e64 v181, 0, v128, s[18:19]
	v_cndmask_b32_e64 v182, 0, v129, s[22:23]
	v_sub_f32_e32 v114, v114, v136
	v_sub_f32_e32 v115, v115, v136
	v_mfma_f32_16x16x32_f16 v[126:129], v[74:77], v[46:49], v[78:81]
	v_add_f32_e32 v74, 0, v122
	v_cndmask_b32_e64 v124, 0, v124, s[12:13]
	v_exp_f32_e32 v114, v114
	v_exp_f32_e32 v115, v115
	v_sub_f32_e32 v116, v116, v136
	v_sub_f32_e32 v117, v117, v136
	v_add_f32_e32 v74, v123, v74
	v_mfma_f32_16x16x32_f16 v[70:73], v[70:73], v[42:45], 0
	v_cndmask_b32_e64 v125, 0, v125, s[14:15]
	v_sub_f32_e32 v118, v118, v136
	v_exp_f32_e32 v116, v116
	v_exp_f32_e32 v117, v117
	v_add_f32_e32 v74, v124, v74
	v_exp_f32_e32 v118, v118
	v_sub_f32_e32 v119, v119, v136
	v_add_f32_e32 v74, v125, v74
	v_exp_f32_e32 v119, v119
	v_sub_f32_e32 v120, v120, v136
	v_sub_f32_e32 v121, v121, v136
	v_add_f32_e32 v74, v173, v74
	v_exp_f32_e32 v120, v120
	v_exp_f32_e32 v121, v121
	v_cndmask_b32_e64 v187, 0, v114, s[28:29]
	v_cndmask_b32_e64 v188, 0, v115, s[34:35]
	v_cvt_pk_f16_f32 v115, v124, v125
	v_cvt_pk_f16_f32 v114, v122, v123
	v_mfma_f32_16x16x32_f16 v[122:125], v[58:61], v[46:49], v[70:73]
	v_add_f32_e32 v58, v180, v74
	v_cndmask_b32_e64 v189, 0, v116, s[36:37]
	v_cndmask_b32_e64 v190, 0, v117, s[38:39]
	v_cvt_pk_f16_f32 v117, v181, v182
	v_cvt_pk_f16_f32 v116, v173, v180
	s_add_i32 s55, s53, 1
	v_add_f32_e32 v58, v181, v58
	v_cndmask_b32_e64 v183, 0, v118, s[20:21]
	s_waitcnt vmcnt(0) lgkmcnt(0)
; #define MFMA16(a, b, c) __builtin_amdgcn_mfma_f32_16x16x32_f16((a), (b), (c), 0, 0, 0)
; __device__ __forceinline__ float shx(float v, int m) { return __shfl_xor(v, m); }
;     ...
;         for (int s_ = 0; s_ < NS; ++s_) {
;             f32x4 s[4];
; #pragma unroll
;             for (int t = 0; t < 4; ++t) { s[t] = MFMA16(ka[2 * t], qf[s_][0], z); s[t] = MFMA16(ka[2 * t + 1], qf[s_][1], s[t]); }
;             if (s_ == NS - 1) {
;                 const half_t* kpA = kf + (size_t)nbA * 2048; const half_t* kpB = kf + (size_t)nbB * 2048;
; #pragma unroll
;                 for (int i = 0; i < 4; ++i) { ka[i] = *(const half8*)(kpA + i * 512); ka[4 + i] = *(const half8*)(kpB + i * 512); }
;             }
;             if (MODE != 1) {
;                 float mx = -1e30f;
; #pragma unroll
;                 for (int t = 0; t < 4; ++t)
; #pragma unroll
;                     for (int r = 0; r < 4; ++r) { if (valid(s_, kbA + 16 * t + 4 * g + r)) mx = fmaxf(mx, s[t][r]); }
;                 if (__ballot(mx > m[s_] + RESC_THR) != 0ull) {
;                     mx = fmaxf(mx, shx(mx, 16)); mx = fmaxf(mx, shx(mx, 32));
;                     const float mn = fmaxf(m[s_], mx); const float corr = __builtin_amdgcn_exp2f(m[s_] - mn); m[s_] = mn; l[s_] = l[s_] * corr;
;                     if (PV) {
; #pragma unroll
;                         for (int dt = 0; dt < 4; ++dt) o[s_][dt] = o[s_][dt] * corr;
;                     }
;                 }
;             }
;             float p[4][4]; float ps = 0.f;
; #pragma unroll
;             for (int t = 0; t < 4; ++t)
; #pragma unroll
;                 for (int r = 0; r < 4; ++r) { p[t][r] = valid(s_, kbA + 16 * t + 4 * g + r) ? __builtin_amdgcn_exp2f(s[t][r] - m[s_]) : 0.f; if (MODE == 1) p[t][r] *= l[s_]; ps += p[t][r]; }
;             if (MODE != 1) l[s_] = l[s_] + ps;
;             if (PV) {
;                 const half8 pfA = {(half_t)p[0][0], (half_t)p[0][1], (half_t)p[0][2], (half_t)p[0][3], (half_t)p[1][0], (half_t)p[1][1], (half_t)p[1][2], (half_t)p[1][3]};
;                 const half8 pfB = {(half_t)p[2][0], (half_t)p[2][1], (half_t)p[2][2], (half_t)p[2][3], (half_t)p[3][0], (half_t)p[3][1], (half_t)p[3][2], (half_t)p[3][3]};
; #pragma unroll
;                 for (int dt = 0; dt < 4; ++dt) { o[s_][dt] = MFMA16(va[dt], pfA, o[s_][dt]); o[s_][dt] = MFMA16(va[4 + dt], pfB, o[s_][dt]); }
;             }
	v_mfma_f32_16x16x32_f16 v[30:33], v[110:113], v[114:117], v[30:33]
	s_cmp_lt_i32 s53, s52
	v_add_f32_e32 v70, v182, v58
	v_cndmask_b32_e64 v184, 0, v119, s[24:25]
	v_mfma_f32_16x16x32_f16 v[26:29], v[102:105], v[114:117], v[26:29]
	s_cselect_b32 s2, s55, s53
	v_cndmask_b32_e64 v185, 0, v120, s[26:27]
	v_cndmask_b32_e64 v186, 0, v121, s[30:31]
	v_mfma_f32_16x16x32_f16 v[22:25], v[94:97], v[114:117], v[22:25]
	s_lshl_b32 s2, s2, 6
	v_cvt_pk_f16_f32 v121, v189, v190
	v_cvt_pk_f16_f32 v120, v187, v188
	v_mfma_f32_16x16x32_f16 v[18:21], v[86:89], v[114:117], v[18:21]
	v_cvt_pk_f16_f32 v119, v185, v186
	v_cvt_pk_f16_f32 v118, v183, v184
	s_add_i32 s54, s2, s51
	v_mfma_f32_16x16x32_f16 v[58:61], v[66:69], v[42:45], 0
	v_add_f32_e32 v66, v183, v70
	v_add_f32_e32 v66, v184, v66
	v_add_f32_e32 v66, v185, v66
	v_mfma_f32_16x16x32_f16 v[30:33], v[106:109], v[118:121], v[30:33]
	s_lshr_b32 s84, s54, 5
	s_add_i32 s2, s84, 1
	s_min_i32 s6, s2, s43
	v_mfma_f32_16x16x32_f16 v[26:29], v[98:101], v[118:121], v[26:29]
	s_lshl_b64 s[2:3], s[84:85], 12
	s_ashr_i32 s7, s6, 31
	v_lshl_add_u64 v[136:137], v[140:141], 0, s[2:3]
	v_mfma_f32_16x16x32_f16 v[22:25], v[90:93], v[118:121], v[22:25]
	s_lshl_b64 s[48:49], s[6:7], 12
	v_lshl_add_u64 v[168:169], v[140:141], 0, s[48:49]
	v_cmp_le_i32_e32 vcc, v150, v148
	v_mfma_f32_16x16x32_f16 v[18:21], v[82:85], v[118:121], v[18:21]
	v_cmp_gt_i32_e64 s[6:7], v150, v149
	s_and_b64 s[38:39], vcc, s[6:7]
	v_cmp_lt_i32_e32 vcc, v150, v148
	v_mfma_f32_16x16x32_f16 v[118:121], v[62:65], v[46:49], v[58:61]
	v_cmp_ge_i32_e64 s[6:7], v150, v149
	s_and_b64 s[36:37], vcc, s[6:7]
	v_cmp_le_i32_e32 vcc, v151, v148
	v_add_f32_e32 v58, v186, v66
	v_add_f32_e32 v58, v187, v58
	v_mfma_f32_16x16x32_f16 v[54:57], v[54:57], v[42:45], 0
	v_add_f32_e32 v58, v188, v58
	v_add_f32_e32 v58, v189, v58
	v_add_f32_e32 v58, v190, v58
	v_add_f32_e32 v138, v138, v58
	v_mfma_f32_16x16x32_f16 v[114:117], v[50:53], v[46:49], v[54:57]
	flat_load_dwordx4 v[78:81], v[136:137]
	flat_load_dwordx4 v[74:77], v[136:137] offset:1024
	flat_load_dwordx4 v[66:69], v[168:169]
	flat_load_dwordx4 v[62:65], v[168:169] offset:1024
	flat_load_dwordx4 v[70:73], v[136:137] offset:2048
	flat_load_dwordx4 v[58:61], v[136:137] offset:3072
	flat_load_dwordx4 v[54:57], v[168:169] offset:2048
	flat_load_dwordx4 v[50:53], v[168:169] offset:3072
	v_max_f32_e32 v136, 0xf149f2ca, v126
	v_cndmask_b32_e64 v136, v172, v136, s[38:39]
	v_max_f32_e32 v137, v136, v127
	v_cndmask_b32_e64 v136, v136, v137, s[36:37]
	v_cmp_gt_i32_e64 s[6:7], v151, v149
	v_max_f32_e32 v137, v136, v128
	s_and_b64 s[34:35], vcc, s[6:7]
	v_cndmask_b32_e64 v136, v136, v137, s[34:35]
	v_cmp_le_i32_e32 vcc, v152, v148
	v_cmp_gt_i32_e64 s[6:7], v152, v149
	v_max_f32_e32 v137, v136, v129
	s_and_b64 s[28:29], vcc, s[6:7]
	v_cndmask_b32_e64 v136, v136, v137, s[28:29]
	v_sub_u32_e32 v137, v147, v150
	s_movk_i32 s6, 0x81
	v_cmp_le_i32_e32 vcc, v155, v148
	v_cmp_gt_i32_e64 s[6:7], s6, v137
	v_max_f32_e32 v137, v136, v122
	s_and_b64 s[30:31], vcc, s[6:7]
	v_cndmask_b32_e64 v136, v136, v137, s[30:31]
	v_cmp_le_i32_e32 vcc, v153, v148
	v_cmp_gt_i32_e64 s[6:7], v153, v149
	v_max_f32_e32 v137, v136, v123
	s_and_b64 s[26:27], vcc, s[6:7]
	v_cndmask_b32_e64 v136, v136, v137, s[26:27]
	v_cmp_le_i32_e32 vcc, v154, v148
	v_cmp_gt_i32_e64 s[6:7], v154, v149
	v_max_f32_e32 v137, v136, v124
	s_and_b64 s[24:25], vcc, s[6:7]
	v_cndmask_b32_e64 v136, v136, v137, s[24:25]
	v_cmp_le_i32_e32 vcc, v156, v148
	v_cmp_gt_i32_e64 s[6:7], v156, v149
	v_max_f32_e32 v137, v136, v125
	s_and_b64 s[20:21], vcc, s[6:7]
	v_cndmask_b32_e64 v136, v136, v137, s[20:21]
	v_cmp_le_i32_e32 vcc, v157, v148
	v_cmp_gt_i32_e64 s[6:7], v157, v149
	v_max_f32_e32 v137, v136, v118
	s_and_b64 s[22:23], vcc, s[6:7]
	v_cndmask_b32_e64 v136, v136, v137, s[22:23]
	v_cmp_le_i32_e32 vcc, v158, v148
	v_cmp_gt_i32_e64 s[6:7], v158, v149
	v_max_f32_e32 v137, v136, v119
	s_and_b64 s[18:19], vcc, s[6:7]
	v_cndmask_b32_e64 v136, v136, v137, s[18:19]
	v_cmp_le_i32_e32 vcc, v159, v148
	v_cmp_gt_i32_e64 s[6:7], v159, v149
	v_max_f32_e32 v137, v136, v120
	s_and_b64 s[16:17], vcc, s[6:7]
	v_cndmask_b32_e64 v136, v136, v137, s[16:17]
	v_cmp_le_i32_e32 vcc, v160, v148
	v_cmp_gt_i32_e64 s[6:7], v160, v149
	v_max_f32_e32 v137, v136, v121
	s_and_b64 s[12:13], vcc, s[6:7]
	v_cndmask_b32_e64 v136, v136, v137, s[12:13]
	v_cmp_le_i32_e32 vcc, v161, v148
	v_cmp_gt_i32_e64 s[6:7], v161, v149
	v_max_f32_e32 v137, v136, v114
	s_and_b64 s[14:15], vcc, s[6:7]
	v_cndmask_b32_e64 v136, v136, v137, s[14:15]
	v_cmp_le_i32_e32 vcc, v162, v148
	v_cmp_gt_i32_e64 s[6:7], v162, v149
	v_max_f32_e32 v137, v136, v115
	s_and_b64 s[10:11], vcc, s[6:7]
	v_cndmask_b32_e64 v136, v136, v137, s[10:11]
	v_cmp_le_i32_e32 vcc, v163, v148
	v_cmp_gt_i32_e64 s[6:7], v163, v149
	v_max_f32_e32 v137, v136, v116
	s_and_b64 s[8:9], vcc, s[6:7]
	v_cndmask_b32_e64 v136, v136, v137, s[8:9]
	v_cmp_le_i32_e32 vcc, v167, v148
	v_cmp_gt_i32_e64 s[6:7], v167, v149
	v_max_f32_e32 v150, v117, v117
	v_max_f32_e32 v137, v136, v150
	s_and_b64 s[6:7], vcc, s[6:7]
	v_cndmask_b32_e64 v136, v136, v137, s[6:7]
	v_add_f32_e32 v137, 0x41400000, v145
	v_cmp_gt_f32_e32 vcc, v136, v137
	s_cbranch_vccz .LBB0_964
	ds_bpermute_b32 v137, v139, v136
	v_max_f32_e32 v136, v136, v136
	s_waitcnt lgkmcnt(0)
	v_max_f32_e32 v137, v137, v137
	v_max_f32_e32 v136, v136, v137
	ds_bpermute_b32 v137, v146, v136
	s_waitcnt lgkmcnt(0)
	v_max3_f32 v151, v145, v136, v137
	v_sub_f32_e32 v136, v145, v151
	v_exp_f32_e32 v150, v136
	v_mov_b32_e32 v145, v151
	v_mov_b64_e32 v[136:137], v[144:145]
	v_mul_f32_e32 v131, v131, v150
	v_pk_mul_f32 v[16:17], v[16:17], v[150:151] op_sel_hi:[1,0]
	v_pk_mul_f32 v[14:15], v[14:15], v[150:151] op_sel_hi:[1,0]
	v_pk_mul_f32 v[12:13], v[12:13], v[150:151] op_sel_hi:[1,0]
	v_pk_mul_f32 v[10:11], v[10:11], v[150:151] op_sel_hi:[1,0]
	v_pk_mul_f32 v[8:9], v[8:9], v[150:151] op_sel_hi:[1,0]
	v_pk_mul_f32 v[6:7], v[6:7], v[150:151] op_sel_hi:[1,0]
	v_pk_mul_f32 v[4:5], v[4:5], v[150:151] op_sel_hi:[1,0]
	v_pk_mul_f32 v[2:3], v[2:3], v[150:151] op_sel_hi:[1,0]
	s_branch .LBB0_965

; #define MFMA16(a, b, c) __builtin_amdgcn_mfma_f32_16x16x32_f16((a), (b), (c), 0, 0, 0)
; __device__ __forceinline__ float shx(float v, int m) { return __shfl_xor(v, m); }
;     ...
;     for (int it = 0; it < nit; ++it) {
;         const int kbN = kbof((it + 1 < nit) ? it + 1 : it);
;         const int nbA = kbN >> 5, nbB = (nbA + 1 <= maxblk) ? nbA + 1 : maxblk;
;         const f32x4 z = {0.f, 0.f, 0.f, 0.f};
; #pragma unroll
;         for (int s_ = 0; s_ < NS; ++s_) {
;             f32x4 s[4];
; #pragma unroll
;             for (int t = 0; t < 4; ++t) { s[t] = MFMA16(ka[2 * t], qf[s_][0], z); s[t] = MFMA16(ka[2 * t + 1], qf[s_][1], s[t]); }
;             if (s_ == NS - 1) {
;                 const half_t* kpA = kf + (size_t)nbA * 2048; const half_t* kpB = kf + (size_t)nbB * 2048;
; #pragma unroll
;                 for (int i = 0; i < 4; ++i) { ka[i] = *(const half8*)(kpA + i * 512); ka[4 + i] = *(const half8*)(kpB + i * 512); }
;             }
;             if (MODE != 1) {
;                 float mx = -1e30f;
; #pragma unroll
;                 for (int t = 0; t < 4; ++t)
; #pragma unroll
;                     for (int r = 0; r < 4; ++r) { if (valid(s_, kbA + 16 * t + 4 * g + r)) mx = fmaxf(mx, s[t][r]); }
;                 if (__ballot(mx > m[s_] + RESC_THR) != 0ull) {
;                     mx = fmaxf(mx, shx(mx, 16)); mx = fmaxf(mx, shx(mx, 32));
;                     const float mn = fmaxf(m[s_], mx); const float corr = __builtin_amdgcn_exp2f(m[s_] - mn); m[s_] = mn; l[s_] = l[s_] * corr;
;                     if (PV) {
; #pragma unroll
;                         for (int dt = 0; dt < 4; ++dt) o[s_][dt] = o[s_][dt] * corr;
;                     }
;                 }
;             }
; __device__ __forceinline__ void c_unit(const ACtx& X, int b, int kvh, int qb, int lane) {
;     ...
;     auto valid = [&](int, int key) { return key <= tq && tq - key <= 127; };
.LBB0_979:
	flat_load_dwordx4 v[130:133], v[106:107]
	flat_load_dwordx4 v[122:125], v[106:107] offset:1024
	flat_load_dwordx4 v[114:117], v[106:107] offset:2048
	s_nop 0
	flat_load_dwordx4 v[106:109], v[106:107] offset:3072
	s_nop 0
	flat_load_dwordx4 v[134:137], v[110:111]
	flat_load_dwordx4 v[126:129], v[110:111] offset:1024
	flat_load_dwordx4 v[118:121], v[110:111] offset:2048
	s_nop 0
	flat_load_dwordx4 v[110:113], v[110:111] offset:3072
	s_waitcnt vmcnt(0) lgkmcnt(0)
	v_mfma_f32_16x16x32_f16 v[138:141], v[90:93], v[50:53], 0
	v_add_u32_e32 v157, s46, v166
	v_cmp_le_i32_e32 vcc, v157, v190
	v_cmp_gt_i32_e64 s[6:7], v157, v192
	v_mfma_f32_16x16x32_f16 v[146:149], v[98:101], v[54:57], v[138:141]
	s_and_b64 s[6:7], vcc, s[6:7]
	v_sub_u32_e32 v159, v157, v190
	s_movk_i32 s2, 0xff7f
	v_cmp_lt_i32_e32 vcc, v157, v190
	v_cmp_lt_i32_e64 s[8:9], s2, v159
	s_nop 2
	v_max_f32_e32 v158, 0xf149f2ca, v146
	v_cndmask_b32_e64 v158, v172, v158, s[6:7]
	v_mfma_f32_16x16x32_f16 v[138:141], v[94:97], v[50:53], 0
	s_and_b64 s[8:9], vcc, s[8:9]
	v_max_f32_e32 v159, v158, v147
	v_cndmask_b32_e64 v158, v158, v159, s[8:9]
	v_add_u32_e32 v159, 2, v157
	v_cmp_le_i32_e32 vcc, v159, v190
	v_cmp_gt_i32_e64 s[10:11], v159, v192
	s_and_b64 s[10:11], vcc, s[10:11]
	v_max_f32_e32 v159, v158, v148
	v_mfma_f32_16x16x32_f16 v[150:153], v[102:105], v[54:57], v[138:141]
	v_cndmask_b32_e64 v158, v158, v159, s[10:11]
	v_add_u32_e32 v159, 3, v157
	v_cmp_le_i32_e32 vcc, v159, v190
	v_cmp_gt_i32_e64 s[12:13], v159, v192
	s_and_b64 s[14:15], vcc, s[12:13]
	v_max_f32_e32 v159, v158, v149
	v_cndmask_b32_e64 v158, v158, v159, s[14:15]
	v_add_u32_e32 v159, 16, v157
	v_cmp_le_i32_e32 vcc, v159, v190
	v_cmp_gt_i32_e64 s[12:13], v159, v192
	s_and_b64 s[12:13], vcc, s[12:13]
	v_max_f32_e32 v159, v158, v150
	v_cndmask_b32_e64 v158, v158, v159, s[12:13]
	v_add_u32_e32 v159, 17, v157
	v_cmp_le_i32_e32 vcc, v159, v190
	v_cmp_gt_i32_e64 s[16:17], v159, v192
	v_mfma_f32_16x16x32_f16 v[138:141], v[86:89], v[50:53], 0
	s_and_b64 s[16:17], vcc, s[16:17]
	v_max_f32_e32 v159, v158, v151
	v_cndmask_b32_e64 v158, v158, v159, s[16:17]
	v_add_u32_e32 v159, 18, v157
	v_cmp_le_i32_e32 vcc, v159, v190
	v_cmp_gt_i32_e64 s[18:19], v159, v192
	s_and_b64 s[18:19], vcc, s[18:19]
	v_max_f32_e32 v159, v158, v152
	v_mfma_f32_16x16x32_f16 v[142:145], v[82:85], v[54:57], v[138:141]
	v_cndmask_b32_e64 v158, v158, v159, s[18:19]
	v_add_u32_e32 v159, 19, v157
	v_cmp_le_i32_e32 vcc, v159, v190
	v_cmp_gt_i32_e64 s[20:21], v159, v192
	s_and_b64 s[22:23], vcc, s[20:21]
	v_max_f32_e32 v159, v158, v153
	v_cndmask_b32_e64 v158, v158, v159, s[22:23]
	v_add_u32_e32 v159, 32, v157
	v_cmp_le_i32_e32 vcc, v159, v190
	v_cmp_gt_i32_e64 s[20:21], v159, v192
	s_and_b64 s[20:21], vcc, s[20:21]
	v_max_f32_e32 v159, v158, v142
	v_cndmask_b32_e64 v158, v158, v159, s[20:21]
	v_add_u32_e32 v159, 33, v157
	v_cmp_le_i32_e32 vcc, v159, v190
	v_cmp_gt_i32_e64 s[24:25], v159, v192
	v_mfma_f32_16x16x32_f16 v[138:141], v[78:81], v[50:53], 0
	s_and_b64 s[24:25], vcc, s[24:25]
	v_max_f32_e32 v159, v158, v143
	v_cndmask_b32_e64 v158, v158, v159, s[24:25]
	v_add_u32_e32 v159, 34, v157
	v_cmp_le_i32_e32 vcc, v159, v190
	v_cmp_gt_i32_e64 s[26:27], v159, v192
	s_and_b64 s[26:27], vcc, s[26:27]
	v_max_f32_e32 v159, v158, v144
	v_mfma_f32_16x16x32_f16 v[138:141], v[74:77], v[54:57], v[138:141]
	v_cndmask_b32_e64 v158, v158, v159, s[26:27]
	v_add_u32_e32 v159, 35, v157
	v_cmp_le_i32_e32 vcc, v159, v190
	v_cmp_gt_i32_e64 s[28:29], v159, v192
	s_and_b64 s[30:31], vcc, s[28:29]
	v_max_f32_e32 v159, v158, v145
	v_cndmask_b32_e64 v158, v158, v159, s[30:31]
	v_add_u32_e32 v159, 48, v157
	v_cmp_le_i32_e32 vcc, v159, v190
	v_cmp_gt_i32_e64 s[28:29], v159, v192
	s_and_b64 s[28:29], vcc, s[28:29]
	v_max_f32_e32 v159, v158, v138
	v_cndmask_b32_e64 v158, v158, v159, s[28:29]
	v_add_u32_e32 v159, 49, v157
	v_cmp_le_i32_e32 vcc, v159, v190
	v_cmp_gt_i32_e64 s[34:35], v159, v192
	s_and_b64 s[34:35], vcc, s[34:35]
	v_max_f32_e32 v159, v158, v139
	v_cndmask_b32_e64 v158, v158, v159, s[34:35]
	v_add_u32_e32 v159, 50, v157
	v_cmp_le_i32_e32 vcc, v159, v190
	v_cmp_gt_i32_e64 s[36:37], v159, v192
	v_max_f32_e32 v160, v140, v140
	s_and_b64 s[36:37], vcc, s[36:37]
	v_max_f32_e32 v159, v158, v160
	v_cndmask_b32_e64 v158, v158, v159, s[36:37]
	v_add_u32_e32 v157, 51, v157
	v_cmp_le_i32_e32 vcc, v157, v190
	v_cmp_gt_i32_e64 s[38:39], v157, v192
	v_max_f32_e32 v159, v141, v141
	s_and_b64 s[38:39], vcc, s[38:39]
	v_max_f32_e32 v157, v158, v159
	v_cndmask_b32_e64 v157, v158, v157, s[38:39]
	v_add_f32_e32 v158, 0x41400000, v154
	v_cmp_gt_f32_e32 vcc, v157, v158
	s_cbranch_vccz .LBB0_981
	ds_bpermute_b32 v158, v173, v157
	v_max_f32_e32 v157, v157, v157
	s_waitcnt lgkmcnt(0)
	v_max_f32_e32 v158, v158, v158
	v_max_f32_e32 v157, v157, v158
	ds_bpermute_b32 v158, v188, v157
	s_waitcnt lgkmcnt(0)
	v_max3_f32 v157, v154, v157, v158
	v_sub_f32_e32 v158, v154, v157
	v_exp_f32_e32 v194, v158
	v_mov_b32_e32 v160, v156
	v_mov_b32_e32 v158, v154
	v_mov_b32_e32 v159, v155
	v_mov_b32_e32 v158, v157
	v_mul_f32_e32 v191, v191, v194
	v_pk_mul_f32 v[48:49], v[48:49], v[194:195] op_sel_hi:[1,0]
	v_pk_mul_f32 v[46:47], v[46:47], v[194:195] op_sel_hi:[1,0]
	v_pk_mul_f32 v[44:45], v[44:45], v[194:195] op_sel_hi:[1,0]
	v_pk_mul_f32 v[42:43], v[42:43], v[194:195] op_sel_hi:[1,0]
	v_pk_mul_f32 v[40:41], v[40:41], v[194:195] op_sel_hi:[1,0]
	v_pk_mul_f32 v[38:39], v[38:39], v[194:195] op_sel_hi:[1,0]
	v_pk_mul_f32 v[36:37], v[36:37], v[194:195] op_sel_hi:[1,0]
	v_pk_mul_f32 v[34:35], v[34:35], v[194:195] op_sel_hi:[1,0]
	v_mov_b32_e32 v154, v157
	s_branch .LBB0_982

; #define MFMA16(a, b, c) __builtin_amdgcn_mfma_f32_16x16x32_f16((a), (b), (c), 0, 0, 0)
; __device__ __forceinline__ float shx(float v, int m) { return __shfl_xor(v, m); }
;     ...
;             for (int t = 0; t < 4; ++t) { s[t] = MFMA16(ka[2 * t], qf[s_][0], z); s[t] = MFMA16(ka[2 * t + 1], qf[s_][1], s[t]); }
;             if (s_ == NS - 1) {
;                 const half_t* kpA = kf + (size_t)nbA * 2048; const half_t* kpB = kf + (size_t)nbB * 2048;
; #pragma unroll
;                 for (int i = 0; i < 4; ++i) { ka[i] = *(const half8*)(kpA + i * 512); ka[4 + i] = *(const half8*)(kpB + i * 512); }
;             }
;             if (MODE != 1) {
;                 float mx = -1e30f;
; #pragma unroll
;                 for (int t = 0; t < 4; ++t)
; #pragma unroll
;                     for (int r = 0; r < 4; ++r) { if (valid(s_, kbA + 16 * t + 4 * g + r)) mx = fmaxf(mx, s[t][r]); }
;                 if (__ballot(mx > m[s_] + RESC_THR) != 0ull) {
;                     mx = fmaxf(mx, shx(mx, 16)); mx = fmaxf(mx, shx(mx, 32));
;                     const float mn = fmaxf(m[s_], mx); const float corr = __builtin_amdgcn_exp2f(m[s_] - mn); m[s_] = mn; l[s_] = l[s_] * corr;
;                     if (PV) {
; #pragma unroll
;                         for (int dt = 0; dt < 4; ++dt) o[s_][dt] = o[s_][dt] * corr;
;                     }
;                 }
;             }
;             float p[4][4]; float ps = 0.f;
; #pragma unroll
;             for (int t = 0; t < 4; ++t)
; #pragma unroll
;                 for (int r = 0; r < 4; ++r) { p[t][r] = valid(s_, kbA + 16 * t + 4 * g + r) ? __builtin_amdgcn_exp2f(s[t][r] - m[s_]) : 0.f; if (MODE == 1) p[t][r] *= l[s_]; ps += p[t][r]; }
;             if (MODE != 1) l[s_] = l[s_] + ps;
;             if (PV) {
;                 const half8 pfA = {(half_t)p[0][0], (half_t)p[0][1], (half_t)p[0][2], (half_t)p[0][3], (half_t)p[1][0], (half_t)p[1][1], (half_t)p[1][2], (half_t)p[1][3]};
;                 const half8 pfB = {(half_t)p[2][0], (half_t)p[2][1], (half_t)p[2][2], (half_t)p[2][3], (half_t)p[3][0], (half_t)p[3][1], (half_t)p[3][2], (half_t)p[3][3]};
; #pragma unroll
;                 for (int dt = 0; dt < 4; ++dt) { o[s_][dt] = MFMA16(va[dt], pfA, o[s_][dt]); o[s_][dt] = MFMA16(va[4 + dt], pfB, o[s_][dt]); }
;             }
.LBB0_982:
	v_sub_f32_e32 v146, v146, v154
	v_sub_f32_e32 v147, v147, v154
	v_sub_f32_e32 v148, v148, v154
	v_sub_f32_e32 v149, v149, v154
	v_exp_f32_e32 v146, v146
	v_exp_f32_e32 v147, v147
	v_exp_f32_e32 v148, v148
	v_exp_f32_e32 v149, v149
	v_cndmask_b32_e64 v193, 0, v146, s[6:7]
	v_cndmask_b32_e64 v194, 0, v147, s[8:9]
	v_cndmask_b32_e64 v195, 0, v148, s[10:11]
	v_cndmask_b32_e64 v196, 0, v149, s[14:15]
	v_sub_f32_e32 v146, v150, v154
	v_sub_f32_e32 v147, v151, v154
	v_sub_f32_e32 v148, v152, v154
	v_sub_f32_e32 v149, v153, v154
	v_exp_f32_e32 v146, v146
	v_exp_f32_e32 v147, v147
	v_exp_f32_e32 v148, v148
	v_exp_f32_e32 v149, v149
	v_sub_f32_e32 v138, v138, v154
	v_sub_f32_e32 v139, v139, v154
	v_sub_f32_e32 v140, v140, v154
	v_sub_f32_e32 v141, v141, v154
	v_exp_f32_e32 v138, v138
	v_exp_f32_e32 v139, v139
	v_exp_f32_e32 v140, v140
	v_exp_f32_e32 v141, v141
	v_cndmask_b32_e64 v197, 0, v146, s[12:13]
	v_cndmask_b32_e64 v208, 0, v147, s[16:17]
	v_cndmask_b32_e64 v209, 0, v148, s[18:19]
	v_cndmask_b32_e64 v210, 0, v149, s[22:23]
	v_cndmask_b32_e64 v215, 0, v138, s[28:29]
	v_cndmask_b32_e64 v216, 0, v139, s[34:35]
	v_cndmask_b32_e64 v217, 0, v140, s[36:37]
	v_cndmask_b32_e64 v218, 0, v141, s[38:39]
	v_cvt_pk_f16_f32 v141, v209, v210
	v_cvt_pk_f16_f32 v140, v197, v208
	v_cvt_pk_f16_f32 v139, v195, v196
	v_cvt_pk_f16_f32 v138, v193, v194
	v_sub_f32_e32 v142, v142, v154
	v_sub_f32_e32 v143, v143, v154
	s_waitcnt vmcnt(0)
	v_mfma_f32_16x16x32_f16 v[46:49], v[130:133], v[138:141], v[46:49]
	v_sub_f32_e32 v144, v144, v154
	v_sub_f32_e32 v145, v145, v154
	v_exp_f32_e32 v142, v142
	v_mfma_f32_16x16x32_f16 v[42:45], v[122:125], v[138:141], v[42:45]
	v_exp_f32_e32 v143, v143
	v_exp_f32_e32 v144, v144
	v_exp_f32_e32 v145, v145
	v_mfma_f32_16x16x32_f16 v[38:41], v[114:117], v[138:141], v[38:41]
	v_cndmask_b32_e64 v211, 0, v142, s[20:21]
	v_cndmask_b32_e64 v212, 0, v143, s[24:25]
	v_cndmask_b32_e64 v213, 0, v144, s[26:27]
	v_mfma_f32_16x16x32_f16 v[34:37], v[106:109], v[138:141], v[34:37]
	v_cndmask_b32_e64 v214, 0, v145, s[30:31]
	v_cvt_pk_f16_f32 v145, v217, v218
	v_cvt_pk_f16_f32 v144, v215, v216
	v_mfma_f32_16x16x32_f16 v[138:141], v[90:93], v[58:61], 0
	v_cvt_pk_f16_f32 v143, v213, v214
	v_cvt_pk_f16_f32 v142, v211, v212
	v_mfma_f32_16x16x32_f16 v[150:153], v[98:101], v[62:65], v[138:141]
	v_mfma_f32_16x16x32_f16 v[138:141], v[94:97], v[58:61], 0
	v_mfma_f32_16x16x32_f16 v[146:149], v[102:105], v[62:65], v[138:141]
	s_nop 5
	v_max_f32_e32 v154, 0xf149f2ca, v150
	v_cndmask_b32_e64 v154, v172, v154, s[6:7]
	v_max_f32_e32 v155, v154, v151
	v_cndmask_b32_e64 v154, v154, v155, s[8:9]
	v_max_f32_e32 v155, v154, v152
	v_cndmask_b32_e64 v154, v154, v155, s[10:11]
	v_max_f32_e32 v155, v154, v153
	v_cndmask_b32_e64 v154, v154, v155, s[14:15]
	v_max_f32_e32 v155, v154, v146
	v_cndmask_b32_e64 v154, v154, v155, s[12:13]
	v_mfma_f32_16x16x32_f16 v[138:141], v[86:89], v[58:61], 0
	v_max_f32_e32 v155, v154, v147
	v_cndmask_b32_e64 v154, v154, v155, s[16:17]
	v_max_f32_e32 v155, v154, v148
	v_mfma_f32_16x16x32_f16 v[46:49], v[134:137], v[142:145], v[46:49]
	v_cndmask_b32_e64 v154, v154, v155, s[18:19]
	v_mfma_f32_16x16x32_f16 v[42:45], v[126:129], v[142:145], v[42:45]
	v_max_f32_e32 v155, v154, v149
	v_cndmask_b32_e64 v154, v154, v155, s[22:23]
	v_mfma_f32_16x16x32_f16 v[38:41], v[118:121], v[142:145], v[38:41]
	v_mfma_f32_16x16x32_f16 v[34:37], v[110:113], v[142:145], v[34:37]
	v_mfma_f32_16x16x32_f16 v[142:145], v[82:85], v[62:65], v[138:141]
	v_mfma_f32_16x16x32_f16 v[138:141], v[78:81], v[58:61], 0
	v_mfma_f32_16x16x32_f16 v[138:141], v[74:77], v[62:65], v[138:141]
	s_nop 5
	v_max_f32_e32 v155, v154, v142
	v_cndmask_b32_e64 v154, v154, v155, s[20:21]
	v_max_f32_e32 v155, v154, v143
	v_cndmask_b32_e64 v154, v154, v155, s[24:25]
	v_max_f32_e32 v155, v154, v144
	v_cndmask_b32_e64 v154, v154, v155, s[26:27]
	v_max_f32_e32 v155, v154, v145
	v_cndmask_b32_e64 v154, v154, v155, s[30:31]
	v_max_f32_e32 v155, v154, v138
	v_cndmask_b32_e64 v154, v154, v155, s[28:29]
	v_max_f32_e32 v155, v154, v139
	v_cndmask_b32_e64 v154, v154, v155, s[34:35]
	v_max_f32_e32 v155, v154, v140
	v_cndmask_b32_e64 v154, v154, v155, s[36:37]
	v_max_f32_e32 v156, v141, v141
	v_max_f32_e32 v155, v154, v156
	v_cndmask_b32_e64 v154, v154, v155, s[38:39]
	v_add_f32_e32 v155, 0x41400000, v159
	v_cmp_gt_f32_e32 vcc, v154, v155
	s_cbranch_vccz .LBB0_984
	ds_bpermute_b32 v155, v173, v154
	v_max_f32_e32 v154, v154, v154
	v_mov_b32_e32 v156, v158
	v_mov_b32_e32 v157, v159
	v_mov_b32_e32 v158, v160
	s_waitcnt lgkmcnt(0)
	v_max_f32_e32 v155, v155, v155
	v_max_f32_e32 v154, v154, v155
	ds_bpermute_b32 v155, v188, v154
	s_waitcnt lgkmcnt(0)
	v_max3_f32 v155, v159, v154, v155
	v_sub_f32_e32 v154, v159, v155
	v_exp_f32_e32 v154, v154
	v_mov_b32_e32 v157, v155
	v_mov_b32_e32 v159, v155
	v_mul_f32_e32 v189, v189, v154
	v_pk_mul_f32 v[32:33], v[32:33], v[154:155] op_sel_hi:[1,0]
	v_pk_mul_f32 v[30:31], v[30:31], v[154:155] op_sel_hi:[1,0]
	v_pk_mul_f32 v[28:29], v[28:29], v[154:155] op_sel_hi:[1,0]
	v_pk_mul_f32 v[26:27], v[26:27], v[154:155] op_sel_hi:[1,0]
	v_pk_mul_f32 v[24:25], v[24:25], v[154:155] op_sel_hi:[1,0]
	v_pk_mul_f32 v[22:23], v[22:23], v[154:155] op_sel_hi:[1,0]
	v_pk_mul_f32 v[20:21], v[20:21], v[154:155] op_sel_hi:[1,0]
	v_pk_mul_f32 v[18:19], v[18:19], v[154:155] op_sel_hi:[1,0]
	s_branch .LBB0_985

; #define MFMA16(a, b, c) __builtin_amdgcn_mfma_f32_16x16x32_f16((a), (b), (c), 0, 0, 0)
; __device__ __forceinline__ float shx(float v, int m) { return __shfl_xor(v, m); }
;     ...
;             for (int t = 0; t < 4; ++t) { s[t] = MFMA16(ka[2 * t], qf[s_][0], z); s[t] = MFMA16(ka[2 * t + 1], qf[s_][1], s[t]); }
;             if (s_ == NS - 1) {
;                 const half_t* kpA = kf + (size_t)nbA * 2048; const half_t* kpB = kf + (size_t)nbB * 2048;
; #pragma unroll
;                 for (int i = 0; i < 4; ++i) { ka[i] = *(const half8*)(kpA + i * 512); ka[4 + i] = *(const half8*)(kpB + i * 512); }
;             }
;             if (MODE != 1) {
;                 float mx = -1e30f;
; #pragma unroll
;                 for (int t = 0; t < 4; ++t)
; #pragma unroll
;                     for (int r = 0; r < 4; ++r) { if (valid(s_, kbA + 16 * t + 4 * g + r)) mx = fmaxf(mx, s[t][r]); }
;                 if (__ballot(mx > m[s_] + RESC_THR) != 0ull) {
;                     mx = fmaxf(mx, shx(mx, 16)); mx = fmaxf(mx, shx(mx, 32));
;                     const float mn = fmaxf(m[s_], mx); const float corr = __builtin_amdgcn_exp2f(m[s_] - mn); m[s_] = mn; l[s_] = l[s_] * corr;
;                     if (PV) {
; #pragma unroll
;                         for (int dt = 0; dt < 4; ++dt) o[s_][dt] = o[s_][dt] * corr;
;                     }
;                 }
;             }
;             float p[4][4]; float ps = 0.f;
; #pragma unroll
;             for (int t = 0; t < 4; ++t)
; #pragma unroll
;                 for (int r = 0; r < 4; ++r) { p[t][r] = valid(s_, kbA + 16 * t + 4 * g + r) ? __builtin_amdgcn_exp2f(s[t][r] - m[s_]) : 0.f; if (MODE == 1) p[t][r] *= l[s_]; ps += p[t][r]; }
;             if (MODE != 1) l[s_] = l[s_] + ps;
;             if (PV) {
;                 const half8 pfA = {(half_t)p[0][0], (half_t)p[0][1], (half_t)p[0][2], (half_t)p[0][3], (half_t)p[1][0], (half_t)p[1][1], (half_t)p[1][2], (half_t)p[1][3]};
;                 const half8 pfB = {(half_t)p[2][0], (half_t)p[2][1], (half_t)p[2][2], (half_t)p[2][3], (half_t)p[3][0], (half_t)p[3][1], (half_t)p[3][2], (half_t)p[3][3]};
; #pragma unroll
;                 for (int dt = 0; dt < 4; ++dt) { o[s_][dt] = MFMA16(va[dt], pfA, o[s_][dt]); o[s_][dt] = MFMA16(va[4 + dt], pfB, o[s_][dt]); }
;             }
.LBB0_985:
	v_sub_f32_e32 v150, v150, v159
	v_sub_f32_e32 v146, v146, v159
	v_exp_f32_e32 v150, v150
	v_exp_f32_e32 v146, v146
	v_sub_f32_e32 v138, v138, v159
	v_exp_f32_e32 v138, v138
	v_sub_f32_e32 v142, v142, v159
	v_cndmask_b32_e64 v219, 0, v150, s[6:7]
	v_sub_f32_e32 v150, v151, v159
	v_cndmask_b32_e64 v223, 0, v146, s[12:13]
	v_sub_f32_e32 v146, v147, v159
	v_exp_f32_e32 v142, v142
	v_exp_f32_e32 v150, v150
	v_exp_f32_e32 v146, v146
	v_cndmask_b32_e64 v231, 0, v138, s[28:29]
	v_sub_f32_e32 v138, v139, v159
	v_exp_f32_e32 v138, v138
	v_cndmask_b32_e64 v227, 0, v142, s[20:21]
	v_sub_f32_e32 v142, v143, v159
	v_cndmask_b32_e64 v220, 0, v150, s[8:9]
	v_sub_f32_e32 v150, v152, v159
	v_cndmask_b32_e64 v224, 0, v146, s[16:17]
	v_sub_f32_e32 v146, v148, v159
	v_exp_f32_e32 v142, v142
	v_exp_f32_e32 v150, v150
	v_exp_f32_e32 v146, v146
	v_cndmask_b32_e64 v232, 0, v138, s[34:35]
	v_sub_f32_e32 v138, v140, v159
	v_exp_f32_e32 v138, v138
	v_cndmask_b32_e64 v228, 0, v142, s[24:25]
	v_sub_f32_e32 v142, v144, v159
	v_cndmask_b32_e64 v221, 0, v150, s[10:11]
	v_sub_f32_e32 v150, v153, v159
	v_cndmask_b32_e64 v225, 0, v146, s[18:19]
	v_sub_f32_e32 v146, v149, v159
	v_exp_f32_e32 v142, v142
	v_exp_f32_e32 v150, v150
	v_exp_f32_e32 v146, v146
	v_cndmask_b32_e64 v233, 0, v138, s[36:37]
	v_sub_f32_e32 v138, v141, v159
	s_add_i32 s47, s45, 1
	v_exp_f32_e32 v138, v138
	s_cmp_lt_i32 s45, s43
	v_mfma_f32_16x16x32_f16 v[90:93], v[90:93], v[66:69], 0
	s_cselect_b32 s2, s47, s45
	v_cndmask_b32_e64 v229, 0, v142, s[26:27]
	v_sub_f32_e32 v142, v145, v159
	s_lshl_b32 s2, s2, 6
	v_cndmask_b32_e64 v222, 0, v150, s[14:15]
	v_cndmask_b32_e64 v226, 0, v146, s[22:23]
	v_exp_f32_e32 v142, v142
	s_add_i32 s46, s2, s44
	v_cndmask_b32_e64 v159, 0, v138, s[38:39]
	v_cvt_pk_f16_f32 v141, v225, v226
	v_cvt_pk_f16_f32 v140, v223, v224
	v_cvt_pk_f16_f32 v139, v221, v222
	v_cvt_pk_f16_f32 v138, v219, v220
	s_lshr_b32 s84, s46, 5
	v_mfma_f32_16x16x32_f16 v[150:153], v[98:101], v[70:73], v[90:93]
	s_min_u32 s33, s84, 0x1fe
	s_lshl_b64 s[2:3], s[84:85], 12
	s_lshl_b32 s33, s33, 12
	v_mfma_f32_16x16x32_f16 v[30:33], v[130:133], v[138:141], v[30:33]
	v_cndmask_b32_e64 v230, 0, v142, s[30:31]
	v_lshl_add_u64 v[160:161], v[184:185], 0, s[2:3]
	s_add_i32 s84, s33, 0x1000
	v_mfma_f32_16x16x32_f16 v[26:29], v[122:125], v[138:141], v[26:29]
	v_cvt_pk_f16_f32 v145, v233, v159
	v_cvt_pk_f16_f32 v144, v231, v232
	v_cvt_pk_f16_f32 v143, v229, v230
	v_mfma_f32_16x16x32_f16 v[22:25], v[114:117], v[138:141], v[22:25]
	v_cvt_pk_f16_f32 v142, v227, v228
	v_lshl_add_u64 v[154:155], v[184:185], 0, s[84:85]
	v_mfma_f32_16x16x32_f16 v[18:21], v[106:109], v[138:141], v[18:21]
	v_mfma_f32_16x16x32_f16 v[90:93], v[94:97], v[66:69], 0
	v_mfma_f32_16x16x32_f16 v[86:89], v[86:89], v[66:69], 0
	v_mfma_f32_16x16x32_f16 v[78:81], v[78:81], v[66:69], 0
	v_mfma_f32_16x16x32_f16 v[30:33], v[134:137], v[142:145], v[30:33]
	v_mfma_f32_16x16x32_f16 v[26:29], v[126:129], v[142:145], v[26:29]
	v_mfma_f32_16x16x32_f16 v[22:25], v[118:121], v[142:145], v[22:25]
	v_mfma_f32_16x16x32_f16 v[18:21], v[110:113], v[142:145], v[18:21]
	v_mfma_f32_16x16x32_f16 v[138:141], v[102:105], v[70:73], v[90:93]
	v_mfma_f32_16x16x32_f16 v[142:145], v[82:85], v[70:73], v[86:89]
	v_mfma_f32_16x16x32_f16 v[146:149], v[74:77], v[70:73], v[78:81]
	s_nop 0
	flat_load_dwordx4 v[90:93], v[160:161]
	flat_load_dwordx4 v[86:89], v[154:155]
	flat_load_dwordx4 v[98:101], v[160:161] offset:1024
	flat_load_dwordx4 v[82:85], v[154:155] offset:1024
	flat_load_dwordx4 v[94:97], v[160:161] offset:2048
	flat_load_dwordx4 v[78:81], v[154:155] offset:2048
	flat_load_dwordx4 v[102:105], v[160:161] offset:3072
	flat_load_dwordx4 v[74:77], v[154:155] offset:3072
	v_max_f32_e32 v154, 0xf149f2ca, v150
	v_cndmask_b32_e64 v154, v172, v154, s[6:7]
	v_max_f32_e32 v155, v154, v151
	v_cndmask_b32_e64 v154, v154, v155, s[8:9]
	v_max_f32_e32 v155, v154, v152
	v_cndmask_b32_e64 v154, v154, v155, s[10:11]
	v_max_f32_e32 v155, v154, v153
	v_cndmask_b32_e64 v154, v154, v155, s[14:15]
	v_max_f32_e32 v155, v154, v138
	v_cndmask_b32_e64 v154, v154, v155, s[12:13]
	v_max_f32_e32 v155, v154, v139
	v_cndmask_b32_e64 v154, v154, v155, s[16:17]
	v_max_f32_e32 v155, v154, v140
	v_cndmask_b32_e64 v154, v154, v155, s[18:19]
	v_max_f32_e32 v155, v154, v141
	v_cndmask_b32_e64 v154, v154, v155, s[22:23]
	v_max_f32_e32 v155, v154, v142
	v_cndmask_b32_e64 v154, v154, v155, s[20:21]
	v_max_f32_e32 v155, v154, v143
	v_cndmask_b32_e64 v154, v154, v155, s[24:25]
	v_max_f32_e32 v155, v154, v144
	v_cndmask_b32_e64 v154, v154, v155, s[26:27]
	v_max_f32_e32 v155, v154, v145
	v_cndmask_b32_e64 v154, v154, v155, s[30:31]
	v_max_f32_e32 v155, v154, v146
	v_cndmask_b32_e64 v154, v154, v155, s[28:29]
	v_max_f32_e32 v155, v154, v147
	v_cndmask_b32_e64 v154, v154, v155, s[34:35]
	v_max_f32_e32 v155, v154, v148
	v_cndmask_b32_e64 v154, v154, v155, s[36:37]
	v_max_f32_e32 v160, v149, v149
	v_max_f32_e32 v155, v154, v160
	v_cndmask_b32_e64 v154, v154, v155, s[38:39]
	v_add_f32_e32 v155, 0x41400000, v158
	v_cmp_gt_f32_e32 vcc, v154, v155
	s_cbranch_vccz .LBB0_987
	ds_bpermute_b32 v155, v173, v154
	v_max_f32_e32 v154, v154, v154
	s_waitcnt lgkmcnt(0)
	v_max_f32_e32 v155, v155, v155
	v_max_f32_e32 v154, v154, v155
	ds_bpermute_b32 v155, v188, v154
	s_waitcnt lgkmcnt(0)
	v_max3_f32 v161, v158, v154, v155
	v_sub_f32_e32 v154, v158, v161
	v_exp_f32_e32 v160, v154
	v_mov_b32_e32 v154, v156
	v_mov_b32_e32 v155, v157
	v_mov_b32_e32 v156, v158
	v_mov_b32_e32 v156, v161
	v_mul_f32_e32 v163, v163, v160
	v_pk_mul_f32 v[16:17], v[16:17], v[160:161] op_sel_hi:[1,0]
	v_pk_mul_f32 v[14:15], v[14:15], v[160:161] op_sel_hi:[1,0]
	v_pk_mul_f32 v[12:13], v[12:13], v[160:161] op_sel_hi:[1,0]
	v_pk_mul_f32 v[10:11], v[10:11], v[160:161] op_sel_hi:[1,0]
	v_pk_mul_f32 v[8:9], v[8:9], v[160:161] op_sel_hi:[1,0]
	v_pk_mul_f32 v[6:7], v[6:7], v[160:161] op_sel_hi:[1,0]
	v_pk_mul_f32 v[4:5], v[4:5], v[160:161] op_sel_hi:[1,0]
	v_pk_mul_f32 v[2:3], v[2:3], v[160:161] op_sel_hi:[1,0]
	v_mov_b32_e32 v158, v161
	s_branch .LBB0_988

; #define MFMA16(a, b, c) __builtin_amdgcn_mfma_f32_16x16x32_f16((a), (b), (c), 0, 0, 0)
; __device__ __forceinline__ float shx(float v, int m) { return __shfl_xor(v, m); }
;     ...
;     for (int it = 0; it < nit; ++it) {
;         const int kbN = kbof((it + 1 < nit) ? it + 1 : it);
;         const int nbA = kbN >> 5, nbB = (nbA + 1 <= maxblk) ? nbA + 1 : maxblk;
;         const f32x4 z = {0.f, 0.f, 0.f, 0.f};
; #pragma unroll
;         for (int s_ = 0; s_ < NS; ++s_) {
;             f32x4 s[4];
; #pragma unroll
;             for (int t = 0; t < 4; ++t) { s[t] = MFMA16(ka[2 * t], qf[s_][0], z); s[t] = MFMA16(ka[2 * t + 1], qf[s_][1], s[t]); }
;             if (s_ == NS - 1) {
;                 const half_t* kpA = kf + (size_t)nbA * 2048; const half_t* kpB = kf + (size_t)nbB * 2048;
; #pragma unroll
;                 for (int i = 0; i < 4; ++i) { ka[i] = *(const half8*)(kpA + i * 512); ka[4 + i] = *(const half8*)(kpB + i * 512); }
;             }
;             if (MODE != 1) {
;                 float mx = -1e30f;
; #pragma unroll
;                 for (int t = 0; t < 4; ++t)
; #pragma unroll
;                     for (int r = 0; r < 4; ++r) { if (valid(s_, kbA + 16 * t + 4 * g + r)) mx = fmaxf(mx, s[t][r]); }
;                 if (__ballot(mx > m[s_] + RESC_THR) != 0ull) {
;                     mx = fmaxf(mx, shx(mx, 16)); mx = fmaxf(mx, shx(mx, 32));
;                     const float mn = fmaxf(m[s_], mx); const float corr = __builtin_amdgcn_exp2f(m[s_] - mn); m[s_] = mn; l[s_] = l[s_] * corr;
;                     if (PV) {
; #pragma unroll
;                         for (int dt = 0; dt < 4; ++dt) o[s_][dt] = o[s_][dt] * corr;
;                     }
;                 }
;             }
; __device__ __forceinline__ void c_unit(const ACtx& X, int b, int kvh, int qb, int lane) {
;     ...
;     auto valid = [&](int, int key) { return key <= tq && tq - key <= 127; };
.LBB0_1008:
	global_load_dwordx4 v[132:135], v[108:109], off
	global_load_dwordx4 v[124:127], v[108:109], off offset:1024
	global_load_dwordx4 v[116:119], v[108:109], off offset:2048
	s_nop 0
	global_load_dwordx4 v[108:111], v[108:109], off offset:3072
	s_nop 0
	global_load_dwordx4 v[136:139], v[112:113], off
	global_load_dwordx4 v[128:131], v[112:113], off offset:1024
	global_load_dwordx4 v[120:123], v[112:113], off offset:2048
	s_nop 0
	global_load_dwordx4 v[112:115], v[112:113], off offset:3072
	s_waitcnt vmcnt(8) lgkmcnt(0)
	v_mfma_f32_16x16x32_f16 v[140:143], v[104:107], v[52:55], 0
	v_add_u32_e32 v2, s46, v166
	v_cmp_le_i32_e32 vcc, v2, v183
	v_cmp_gt_i32_e64 s[6:7], v2, v190
	v_mfma_f32_16x16x32_f16 v[148:151], v[96:99], v[56:59], v[140:143]
	s_and_b64 s[6:7], vcc, s[6:7]
	v_sub_u32_e32 v159, v2, v183
	s_movk_i32 s2, 0xff7f
	v_cmp_lt_i32_e32 vcc, v2, v183
	v_cmp_lt_i32_e64 s[8:9], s2, v159
	s_nop 2
	v_max_f32_e32 v3, 0xf149f2ca, v148
	v_cndmask_b32_e64 v3, v172, v3, s[6:7]
	v_mfma_f32_16x16x32_f16 v[140:143], v[100:103], v[52:55], 0
	s_and_b64 s[8:9], vcc, s[8:9]
	v_max_f32_e32 v159, v3, v149
	v_cndmask_b32_e64 v3, v3, v159, s[8:9]
	v_add_u32_e32 v159, 2, v2
	v_cmp_le_i32_e32 vcc, v159, v183
	v_cmp_gt_i32_e64 s[10:11], v159, v190
	s_and_b64 s[10:11], vcc, s[10:11]
	v_max_f32_e32 v159, v3, v150
	v_mfma_f32_16x16x32_f16 v[152:155], v[92:95], v[56:59], v[140:143]
	v_cndmask_b32_e64 v3, v3, v159, s[10:11]
	v_add_u32_e32 v159, 3, v2
	v_cmp_le_i32_e32 vcc, v159, v183
	v_cmp_gt_i32_e64 s[12:13], v159, v190
	s_and_b64 s[14:15], vcc, s[12:13]
	v_max_f32_e32 v159, v3, v151
	v_cndmask_b32_e64 v3, v3, v159, s[14:15]
	v_add_u32_e32 v159, 16, v2
	v_cmp_le_i32_e32 vcc, v159, v183
	v_cmp_gt_i32_e64 s[12:13], v159, v190
	s_and_b64 s[12:13], vcc, s[12:13]
	v_max_f32_e32 v159, v3, v152
	v_cndmask_b32_e64 v3, v3, v159, s[12:13]
	v_add_u32_e32 v159, 17, v2
	v_cmp_le_i32_e32 vcc, v159, v183
	v_cmp_gt_i32_e64 s[16:17], v159, v190
	v_mfma_f32_16x16x32_f16 v[140:143], v[88:91], v[52:55], 0
	s_and_b64 s[16:17], vcc, s[16:17]
	v_max_f32_e32 v159, v3, v153
	v_cndmask_b32_e64 v3, v3, v159, s[16:17]
	v_add_u32_e32 v159, 18, v2
	v_cmp_le_i32_e32 vcc, v159, v183
	v_cmp_gt_i32_e64 s[18:19], v159, v190
	s_and_b64 s[18:19], vcc, s[18:19]
	v_max_f32_e32 v159, v3, v154
	v_mfma_f32_16x16x32_f16 v[144:147], v[84:87], v[56:59], v[140:143]
	v_cndmask_b32_e64 v3, v3, v159, s[18:19]
	v_add_u32_e32 v159, 19, v2
	v_cmp_le_i32_e32 vcc, v159, v183
	v_cmp_gt_i32_e64 s[20:21], v159, v190
	s_and_b64 s[22:23], vcc, s[20:21]
	v_max_f32_e32 v159, v3, v155
	v_cndmask_b32_e64 v3, v3, v159, s[22:23]
	v_add_u32_e32 v159, 32, v2
	v_cmp_le_i32_e32 vcc, v159, v183
	v_cmp_gt_i32_e64 s[20:21], v159, v190
	s_and_b64 s[20:21], vcc, s[20:21]
	v_max_f32_e32 v159, v3, v144
	v_cndmask_b32_e64 v3, v3, v159, s[20:21]
	v_add_u32_e32 v159, 33, v2
	v_cmp_le_i32_e32 vcc, v159, v183
	v_cmp_gt_i32_e64 s[24:25], v159, v190
	v_mfma_f32_16x16x32_f16 v[140:143], v[80:83], v[52:55], 0
	s_and_b64 s[24:25], vcc, s[24:25]
	v_max_f32_e32 v159, v3, v145
	v_cndmask_b32_e64 v3, v3, v159, s[24:25]
	v_add_u32_e32 v159, 34, v2
	v_cmp_le_i32_e32 vcc, v159, v183
	v_cmp_gt_i32_e64 s[26:27], v159, v190
	s_and_b64 s[26:27], vcc, s[26:27]
	v_max_f32_e32 v159, v3, v146
	v_mfma_f32_16x16x32_f16 v[140:143], v[76:79], v[56:59], v[140:143]
	v_cndmask_b32_e64 v3, v3, v159, s[26:27]
	v_add_u32_e32 v159, 35, v2
	v_cmp_le_i32_e32 vcc, v159, v183
	v_cmp_gt_i32_e64 s[28:29], v159, v190
	s_and_b64 s[30:31], vcc, s[28:29]
	v_max_f32_e32 v159, v3, v147
	v_cndmask_b32_e64 v3, v3, v159, s[30:31]
	v_add_u32_e32 v159, 48, v2
	v_cmp_le_i32_e32 vcc, v159, v183
	v_cmp_gt_i32_e64 s[28:29], v159, v190
	s_and_b64 s[28:29], vcc, s[28:29]
	v_max_f32_e32 v159, v3, v140
	v_cndmask_b32_e64 v3, v3, v159, s[28:29]
	v_add_u32_e32 v159, 49, v2
	v_cmp_le_i32_e32 vcc, v159, v183
	v_cmp_gt_i32_e64 s[34:35], v159, v190
	s_and_b64 s[34:35], vcc, s[34:35]
	v_max_f32_e32 v159, v3, v141
	v_cndmask_b32_e64 v3, v3, v159, s[34:35]
	v_add_u32_e32 v159, 50, v2
	v_cmp_le_i32_e32 vcc, v159, v183
	v_cmp_gt_i32_e64 s[36:37], v159, v190
	v_max_f32_e32 v160, v142, v142
	s_and_b64 s[36:37], vcc, s[36:37]
	v_max_f32_e32 v159, v3, v160
	v_cndmask_b32_e64 v3, v3, v159, s[36:37]
	v_add_u32_e32 v2, 51, v2
	v_cmp_le_i32_e32 vcc, v2, v183
	v_cmp_gt_i32_e64 s[38:39], v2, v190
	v_max_f32_e32 v159, v143, v143
	s_and_b64 s[38:39], vcc, s[38:39]
	v_max_f32_e32 v2, v3, v159
	v_cndmask_b32_e64 v2, v3, v2, s[38:39]
	v_add_f32_e32 v3, 0x41400000, v156
	v_cmp_gt_f32_e32 vcc, v2, v3
	s_cbranch_vccz .LBB0_1010
	v_and_b32_e32 v159, 64, v204
	v_xor_b32_e32 v3, 16, v204
	v_add_u32_e32 v159, 64, v159
	v_cmp_lt_i32_e32 vcc, v3, v159
	v_xor_b32_e32 v160, 32, v204
	s_nop 0
	v_cndmask_b32_e32 v3, v204, v3, vcc
	v_lshlrev_b32_e32 v3, 2, v3
	ds_bpermute_b32 v3, v3, v2
	v_max_f32_e32 v2, v2, v2
	v_cmp_lt_i32_e32 vcc, v160, v159
	s_waitcnt lgkmcnt(0)
	v_max_f32_e32 v3, v3, v3
	v_max_f32_e32 v2, v2, v3
	v_cndmask_b32_e32 v3, v204, v160, vcc
	v_lshlrev_b32_e32 v3, 2, v3
	ds_bpermute_b32 v3, v3, v2
	v_mov_b32_e32 v162, v158
	v_mov_b32_e32 v160, v156
	v_mov_b32_e32 v161, v157
	s_waitcnt lgkmcnt(0)
	v_max3_f32 v3, v156, v2, v3
	v_sub_f32_e32 v2, v156, v3
	v_exp_f32_e32 v2, v2
	v_mov_b32_e32 v160, v3
	v_mov_b32_e32 v156, v3
	v_mul_f32_e32 v0, v0, v2
	v_pk_mul_f32 v[50:51], v[50:51], v[2:3] op_sel_hi:[1,0]
	v_pk_mul_f32 v[48:49], v[48:49], v[2:3] op_sel_hi:[1,0]
	v_pk_mul_f32 v[46:47], v[46:47], v[2:3] op_sel_hi:[1,0]
	v_pk_mul_f32 v[44:45], v[44:45], v[2:3] op_sel_hi:[1,0]
	v_pk_mul_f32 v[42:43], v[42:43], v[2:3] op_sel_hi:[1,0]
	v_pk_mul_f32 v[40:41], v[40:41], v[2:3] op_sel_hi:[1,0]
	v_pk_mul_f32 v[38:39], v[38:39], v[2:3] op_sel_hi:[1,0]
	v_pk_mul_f32 v[36:37], v[36:37], v[2:3] op_sel_hi:[1,0]
	s_branch .LBB0_1011

; #define MFMA16(a, b, c) __builtin_amdgcn_mfma_f32_16x16x32_f16((a), (b), (c), 0, 0, 0)
; __device__ __forceinline__ float shx(float v, int m) { return __shfl_xor(v, m); }
;     ...
;             for (int t = 0; t < 4; ++t) { s[t] = MFMA16(ka[2 * t], qf[s_][0], z); s[t] = MFMA16(ka[2 * t + 1], qf[s_][1], s[t]); }
;             if (s_ == NS - 1) {
;                 const half_t* kpA = kf + (size_t)nbA * 2048; const half_t* kpB = kf + (size_t)nbB * 2048;
; #pragma unroll
;                 for (int i = 0; i < 4; ++i) { ka[i] = *(const half8*)(kpA + i * 512); ka[4 + i] = *(const half8*)(kpB + i * 512); }
;             }
;             if (MODE != 1) {
;                 float mx = -1e30f;
; #pragma unroll
;                 for (int t = 0; t < 4; ++t)
; #pragma unroll
;                     for (int r = 0; r < 4; ++r) { if (valid(s_, kbA + 16 * t + 4 * g + r)) mx = fmaxf(mx, s[t][r]); }
;                 if (__ballot(mx > m[s_] + RESC_THR) != 0ull) {
;                     mx = fmaxf(mx, shx(mx, 16)); mx = fmaxf(mx, shx(mx, 32));
;                     const float mn = fmaxf(m[s_], mx); const float corr = __builtin_amdgcn_exp2f(m[s_] - mn); m[s_] = mn; l[s_] = l[s_] * corr;
;                     if (PV) {
; #pragma unroll
;                         for (int dt = 0; dt < 4; ++dt) o[s_][dt] = o[s_][dt] * corr;
;                     }
;                 }
;             }
;             float p[4][4]; float ps = 0.f;
; #pragma unroll
;             for (int t = 0; t < 4; ++t)
; #pragma unroll
;                 for (int r = 0; r < 4; ++r) { p[t][r] = valid(s_, kbA + 16 * t + 4 * g + r) ? __builtin_amdgcn_exp2f(s[t][r] - m[s_]) : 0.f; if (MODE == 1) p[t][r] *= l[s_]; ps += p[t][r]; }
;             if (MODE != 1) l[s_] = l[s_] + ps;
;             if (PV) {
;                 const half8 pfA = {(half_t)p[0][0], (half_t)p[0][1], (half_t)p[0][2], (half_t)p[0][3], (half_t)p[1][0], (half_t)p[1][1], (half_t)p[1][2], (half_t)p[1][3]};
;                 const half8 pfB = {(half_t)p[2][0], (half_t)p[2][1], (half_t)p[2][2], (half_t)p[2][3], (half_t)p[3][0], (half_t)p[3][1], (half_t)p[3][2], (half_t)p[3][3]};
; #pragma unroll
;                 for (int dt = 0; dt < 4; ++dt) { o[s_][dt] = MFMA16(va[dt], pfA, o[s_][dt]); o[s_][dt] = MFMA16(va[4 + dt], pfB, o[s_][dt]); }
;             }
.LBB0_1011:
	v_sub_f32_e32 v2, v148, v156
	v_sub_f32_e32 v3, v149, v156
	v_exp_f32_e32 v2, v2
	v_exp_f32_e32 v3, v3
	v_sub_f32_e32 v148, v150, v156
	v_sub_f32_e32 v149, v151, v156
	v_cndmask_b32_e64 v191, 0, v2, s[6:7]
	v_cndmask_b32_e64 v192, 0, v3, s[8:9]
	v_sub_f32_e32 v2, v152, v156
	v_sub_f32_e32 v3, v153, v156
	v_exp_f32_e32 v2, v2
	v_exp_f32_e32 v3, v3
	v_exp_f32_e32 v148, v148
	v_exp_f32_e32 v149, v149
	v_cndmask_b32_e64 v195, 0, v2, s[12:13]
	v_cndmask_b32_e64 v196, 0, v3, s[16:17]
	v_sub_f32_e32 v2, v144, v156
	v_sub_f32_e32 v3, v145, v156
	v_exp_f32_e32 v2, v2
	v_exp_f32_e32 v3, v3
	v_cndmask_b32_e64 v193, 0, v148, s[10:11]
	v_cndmask_b32_e64 v194, 0, v149, s[14:15]
	v_sub_f32_e32 v148, v154, v156
	v_sub_f32_e32 v149, v155, v156
	v_exp_f32_e32 v148, v148
	v_exp_f32_e32 v149, v149
	v_cndmask_b32_e64 v209, 0, v2, s[20:21]
	v_cndmask_b32_e64 v210, 0, v3, s[24:25]
	v_sub_f32_e32 v2, v140, v156
	v_sub_f32_e32 v3, v141, v156
	v_sub_f32_e32 v140, v142, v156
	v_sub_f32_e32 v141, v143, v156
	v_exp_f32_e32 v140, v140
	v_exp_f32_e32 v141, v141
	v_cndmask_b32_e64 v197, 0, v148, s[18:19]
	v_cndmask_b32_e64 v208, 0, v149, s[22:23]
	v_cndmask_b32_e64 v215, 0, v140, s[36:37]
	v_cndmask_b32_e64 v216, 0, v141, s[38:39]
	v_cvt_pk_f16_f32 v143, v197, v208
	v_cvt_pk_f16_f32 v142, v195, v196
	v_cvt_pk_f16_f32 v141, v193, v194
	v_cvt_pk_f16_f32 v140, v191, v192
	v_exp_f32_e32 v2, v2
	v_exp_f32_e32 v3, v3
	s_waitcnt vmcnt(0)
	v_mfma_f32_16x16x32_f16 v[48:51], v[132:135], v[140:143], v[48:51]
	v_sub_f32_e32 v144, v146, v156
	v_cndmask_b32_e64 v213, 0, v2, s[28:29]
	v_cndmask_b32_e64 v214, 0, v3, s[34:35]
	v_mfma_f32_16x16x32_f16 v[44:47], v[124:127], v[140:143], v[44:47]
	v_sub_f32_e32 v145, v147, v156
	v_exp_f32_e32 v144, v144
	v_exp_f32_e32 v145, v145
	v_mfma_f32_16x16x32_f16 v[40:43], v[116:119], v[140:143], v[40:43]
	v_cvt_pk_f16_f32 v147, v215, v216
	v_cndmask_b32_e64 v211, 0, v144, s[26:27]
	v_cndmask_b32_e64 v212, 0, v145, s[30:31]
	v_mfma_f32_16x16x32_f16 v[36:39], v[108:111], v[140:143], v[36:39]
	v_cvt_pk_f16_f32 v146, v213, v214
	v_cvt_pk_f16_f32 v145, v211, v212
	v_cvt_pk_f16_f32 v144, v209, v210
	v_mfma_f32_16x16x32_f16 v[140:143], v[104:107], v[60:63], 0
	v_mfma_f32_16x16x32_f16 v[152:155], v[96:99], v[64:67], v[140:143]
	v_mfma_f32_16x16x32_f16 v[140:143], v[100:103], v[60:63], 0
	v_mfma_f32_16x16x32_f16 v[148:151], v[92:95], v[64:67], v[140:143]
	s_nop 5
	v_max_f32_e32 v2, 0xf149f2ca, v152
	v_cndmask_b32_e64 v2, v172, v2, s[6:7]
	v_max_f32_e32 v3, v2, v153
	v_cndmask_b32_e64 v2, v2, v3, s[8:9]
	v_max_f32_e32 v3, v2, v154
	v_cndmask_b32_e64 v2, v2, v3, s[10:11]
	v_max_f32_e32 v3, v2, v155
	v_cndmask_b32_e64 v2, v2, v3, s[14:15]
	v_max_f32_e32 v3, v2, v148
	v_cndmask_b32_e64 v2, v2, v3, s[12:13]
	v_mfma_f32_16x16x32_f16 v[140:143], v[88:91], v[60:63], 0
	v_max_f32_e32 v3, v2, v149
	v_cndmask_b32_e64 v2, v2, v3, s[16:17]
	v_max_f32_e32 v3, v2, v150
	v_mfma_f32_16x16x32_f16 v[48:51], v[136:139], v[144:147], v[48:51]
	v_cndmask_b32_e64 v2, v2, v3, s[18:19]
	v_mfma_f32_16x16x32_f16 v[44:47], v[128:131], v[144:147], v[44:47]
	v_max_f32_e32 v3, v2, v151
	v_cndmask_b32_e64 v2, v2, v3, s[22:23]
	v_mfma_f32_16x16x32_f16 v[40:43], v[120:123], v[144:147], v[40:43]
	v_mfma_f32_16x16x32_f16 v[36:39], v[112:115], v[144:147], v[36:39]
	v_mfma_f32_16x16x32_f16 v[144:147], v[84:87], v[64:67], v[140:143]
	v_mfma_f32_16x16x32_f16 v[140:143], v[80:83], v[60:63], 0
	v_mfma_f32_16x16x32_f16 v[140:143], v[76:79], v[64:67], v[140:143]
	s_nop 5
	v_max_f32_e32 v3, v2, v144
	v_cndmask_b32_e64 v2, v2, v3, s[20:21]
	v_max_f32_e32 v3, v2, v145
	v_cndmask_b32_e64 v2, v2, v3, s[24:25]
	v_max_f32_e32 v3, v2, v146
	v_cndmask_b32_e64 v2, v2, v3, s[26:27]
	v_max_f32_e32 v3, v2, v147
	v_cndmask_b32_e64 v2, v2, v3, s[30:31]
	v_max_f32_e32 v3, v2, v140
	v_cndmask_b32_e64 v2, v2, v3, s[28:29]
	v_max_f32_e32 v3, v2, v141
	v_cndmask_b32_e64 v2, v2, v3, s[34:35]
	v_max_f32_e32 v3, v2, v142
	v_cndmask_b32_e64 v2, v2, v3, s[36:37]
	v_max_f32_e32 v156, v143, v143
	v_max_f32_e32 v3, v2, v156
	v_cndmask_b32_e64 v2, v2, v3, s[38:39]
	v_add_f32_e32 v3, 0x41400000, v161
	v_cmp_gt_f32_e32 vcc, v2, v3
	s_cbranch_vccz .LBB0_1013
	v_and_b32_e32 v156, 64, v204
	v_xor_b32_e32 v3, 16, v204
	v_add_u32_e32 v156, 64, v156
	v_cmp_lt_i32_e32 vcc, v3, v156
	v_xor_b32_e32 v157, 32, v204
	v_mov_b32_e32 v158, v160
	v_cndmask_b32_e32 v3, v204, v3, vcc
	v_lshlrev_b32_e32 v3, 2, v3
	ds_bpermute_b32 v3, v3, v2
	v_max_f32_e32 v2, v2, v2
	v_cmp_lt_i32_e32 vcc, v157, v156
	v_mov_b32_e32 v159, v161
	v_mov_b32_e32 v160, v162
	s_waitcnt lgkmcnt(0)
	v_max_f32_e32 v3, v3, v3
	v_max_f32_e32 v2, v2, v3
	v_cndmask_b32_e32 v3, v204, v157, vcc
	v_lshlrev_b32_e32 v3, 2, v3
	ds_bpermute_b32 v3, v3, v2
	s_waitcnt lgkmcnt(0)
	v_max3_f32 v3, v161, v2, v3
	v_sub_f32_e32 v2, v161, v3
	v_exp_f32_e32 v2, v2
	v_mov_b32_e32 v159, v3
	v_mov_b32_e32 v161, v3
	v_mul_f32_e32 v173, v173, v2
	v_pk_mul_f32 v[34:35], v[34:35], v[2:3] op_sel_hi:[1,0]
	v_pk_mul_f32 v[32:33], v[32:33], v[2:3] op_sel_hi:[1,0]
	v_pk_mul_f32 v[30:31], v[30:31], v[2:3] op_sel_hi:[1,0]
	v_pk_mul_f32 v[28:29], v[28:29], v[2:3] op_sel_hi:[1,0]
	v_pk_mul_f32 v[26:27], v[26:27], v[2:3] op_sel_hi:[1,0]
	v_pk_mul_f32 v[24:25], v[24:25], v[2:3] op_sel_hi:[1,0]
	v_pk_mul_f32 v[22:23], v[22:23], v[2:3] op_sel_hi:[1,0]
	v_pk_mul_f32 v[20:21], v[20:21], v[2:3] op_sel_hi:[1,0]
	s_branch .LBB0_1014

; #define MFMA16(a, b, c) __builtin_amdgcn_mfma_f32_16x16x32_f16((a), (b), (c), 0, 0, 0)
; __device__ __forceinline__ float shx(float v, int m) { return __shfl_xor(v, m); }
;     ...
;             for (int t = 0; t < 4; ++t) { s[t] = MFMA16(ka[2 * t], qf[s_][0], z); s[t] = MFMA16(ka[2 * t + 1], qf[s_][1], s[t]); }
;             if (s_ == NS - 1) {
;                 const half_t* kpA = kf + (size_t)nbA * 2048; const half_t* kpB = kf + (size_t)nbB * 2048;
; #pragma unroll
;                 for (int i = 0; i < 4; ++i) { ka[i] = *(const half8*)(kpA + i * 512); ka[4 + i] = *(const half8*)(kpB + i * 512); }
;             }
;             if (MODE != 1) {
;                 float mx = -1e30f;
; #pragma unroll
;                 for (int t = 0; t < 4; ++t)
; #pragma unroll
;                     for (int r = 0; r < 4; ++r) { if (valid(s_, kbA + 16 * t + 4 * g + r)) mx = fmaxf(mx, s[t][r]); }
;                 if (__ballot(mx > m[s_] + RESC_THR) != 0ull) {
;                     mx = fmaxf(mx, shx(mx, 16)); mx = fmaxf(mx, shx(mx, 32));
;                     const float mn = fmaxf(m[s_], mx); const float corr = __builtin_amdgcn_exp2f(m[s_] - mn); m[s_] = mn; l[s_] = l[s_] * corr;
;                     if (PV) {
; #pragma unroll
;                         for (int dt = 0; dt < 4; ++dt) o[s_][dt] = o[s_][dt] * corr;
;                     }
;                 }
;             }
;             float p[4][4]; float ps = 0.f;
; #pragma unroll
;             for (int t = 0; t < 4; ++t)
; #pragma unroll
;                 for (int r = 0; r < 4; ++r) { p[t][r] = valid(s_, kbA + 16 * t + 4 * g + r) ? __builtin_amdgcn_exp2f(s[t][r] - m[s_]) : 0.f; if (MODE == 1) p[t][r] *= l[s_]; ps += p[t][r]; }
;             if (MODE != 1) l[s_] = l[s_] + ps;
;             if (PV) {
;                 const half8 pfA = {(half_t)p[0][0], (half_t)p[0][1], (half_t)p[0][2], (half_t)p[0][3], (half_t)p[1][0], (half_t)p[1][1], (half_t)p[1][2], (half_t)p[1][3]};
;                 const half8 pfB = {(half_t)p[2][0], (half_t)p[2][1], (half_t)p[2][2], (half_t)p[2][3], (half_t)p[3][0], (half_t)p[3][1], (half_t)p[3][2], (half_t)p[3][3]};
; #pragma unroll
;                 for (int dt = 0; dt < 4; ++dt) { o[s_][dt] = MFMA16(va[dt], pfA, o[s_][dt]); o[s_][dt] = MFMA16(va[4 + dt], pfB, o[s_][dt]); }
;             }
.LBB0_1014:
	v_sub_f32_e32 v152, v152, v161
	v_sub_f32_e32 v148, v148, v161
	v_exp_f32_e32 v152, v152
	v_exp_f32_e32 v148, v148
	v_sub_f32_e32 v140, v140, v161
	v_exp_f32_e32 v140, v140
	v_sub_f32_e32 v144, v144, v161
	v_cndmask_b32_e64 v162, 0, v152, s[6:7]
	v_sub_f32_e32 v152, v153, v161
	v_cndmask_b32_e64 v220, 0, v148, s[12:13]
	v_sub_f32_e32 v148, v149, v161
	v_exp_f32_e32 v144, v144
	v_exp_f32_e32 v152, v152
	v_exp_f32_e32 v148, v148
	v_cndmask_b32_e64 v228, 0, v140, s[28:29]
	v_sub_f32_e32 v140, v141, v161
	v_exp_f32_e32 v140, v140
	v_cndmask_b32_e64 v224, 0, v144, s[20:21]
	v_sub_f32_e32 v144, v145, v161
	v_cndmask_b32_e64 v217, 0, v152, s[8:9]
	v_sub_f32_e32 v152, v154, v161
	v_cndmask_b32_e64 v221, 0, v148, s[16:17]
	v_sub_f32_e32 v148, v150, v161
	v_exp_f32_e32 v144, v144
	v_exp_f32_e32 v152, v152
	v_exp_f32_e32 v148, v148
	v_cndmask_b32_e64 v229, 0, v140, s[34:35]
	v_sub_f32_e32 v140, v142, v161
	v_exp_f32_e32 v140, v140
	v_cndmask_b32_e64 v225, 0, v144, s[24:25]
	v_sub_f32_e32 v144, v146, v161
	v_cndmask_b32_e64 v218, 0, v152, s[10:11]
	v_sub_f32_e32 v152, v155, v161
	v_cndmask_b32_e64 v222, 0, v148, s[18:19]
	v_sub_f32_e32 v148, v151, v161
	v_exp_f32_e32 v144, v144
	v_exp_f32_e32 v152, v152
	v_exp_f32_e32 v148, v148
	v_cndmask_b32_e64 v230, 0, v140, s[36:37]
	v_sub_f32_e32 v140, v143, v161
	s_add_i32 s47, s45, 1
	v_exp_f32_e32 v140, v140
	s_cmp_lt_i32 s45, s43
	v_mfma_f32_16x16x32_f16 v[104:107], v[104:107], v[68:71], 0
	s_cselect_b32 s2, s47, s45
	v_cndmask_b32_e64 v226, 0, v144, s[26:27]
	v_sub_f32_e32 v144, v147, v161
	s_lshl_b32 s2, s2, 6
	v_cndmask_b32_e64 v219, 0, v152, s[14:15]
	v_cndmask_b32_e64 v223, 0, v148, s[22:23]
	v_exp_f32_e32 v144, v144
	s_add_i32 s46, s2, s44
	v_cndmask_b32_e64 v161, 0, v140, s[38:39]
	v_cvt_pk_f16_f32 v143, v222, v223
	v_cvt_pk_f16_f32 v142, v220, v221
	v_cvt_pk_f16_f32 v141, v218, v219
	v_cvt_pk_f16_f32 v140, v162, v217
	s_lshr_b32 s84, s46, 5
	v_mfma_f32_16x16x32_f16 v[152:155], v[96:99], v[72:75], v[104:107]
	s_min_u32 s33, s84, 0x1fe
	s_lshl_b64 s[2:3], s[84:85], 12
	s_lshl_b32 s33, s33, 12
	v_mfma_f32_16x16x32_f16 v[32:35], v[132:135], v[140:143], v[32:35]
	v_cndmask_b32_e64 v227, 0, v144, s[30:31]
	v_lshl_add_u64 v[156:157], v[186:187], 0, s[2:3]
	s_add_i32 s84, s33, 0x1000
	v_mfma_f32_16x16x32_f16 v[28:31], v[124:127], v[140:143], v[28:31]
	v_cvt_pk_f16_f32 v147, v230, v161
	v_cvt_pk_f16_f32 v146, v228, v229
	v_cvt_pk_f16_f32 v145, v226, v227
	v_mfma_f32_16x16x32_f16 v[24:27], v[116:119], v[140:143], v[24:27]
	v_cvt_pk_f16_f32 v144, v224, v225
	v_lshl_add_u64 v[2:3], v[186:187], 0, s[84:85]
	v_mfma_f32_16x16x32_f16 v[20:23], v[108:111], v[140:143], v[20:23]
	v_mfma_f32_16x16x32_f16 v[96:99], v[100:103], v[68:71], 0
	v_mfma_f32_16x16x32_f16 v[88:91], v[88:91], v[68:71], 0
	v_mfma_f32_16x16x32_f16 v[80:83], v[80:83], v[68:71], 0
	v_mfma_f32_16x16x32_f16 v[32:35], v[136:139], v[144:147], v[32:35]
	v_mfma_f32_16x16x32_f16 v[28:31], v[128:131], v[144:147], v[28:31]
	v_mfma_f32_16x16x32_f16 v[24:27], v[120:123], v[144:147], v[24:27]
	v_mfma_f32_16x16x32_f16 v[20:23], v[112:115], v[144:147], v[20:23]
	v_mfma_f32_16x16x32_f16 v[140:143], v[92:95], v[72:75], v[96:99]
	v_mfma_f32_16x16x32_f16 v[144:147], v[84:87], v[72:75], v[88:91]
	v_mfma_f32_16x16x32_f16 v[148:151], v[76:79], v[72:75], v[80:83]
	global_load_dwordx4 v[104:107], v[156:157], off
	s_nop 0
	global_load_dwordx4 v[88:91], v[2:3], off
	global_load_dwordx4 v[96:99], v[156:157], off offset:1024
	global_load_dwordx4 v[84:87], v[2:3], off offset:1024
	global_load_dwordx4 v[100:103], v[156:157], off offset:2048
	global_load_dwordx4 v[80:83], v[2:3], off offset:2048
	global_load_dwordx4 v[92:95], v[156:157], off offset:3072
	global_load_dwordx4 v[76:79], v[2:3], off offset:3072
	v_max_f32_e32 v2, 0xf149f2ca, v152
	v_cndmask_b32_e64 v2, v172, v2, s[6:7]
	v_max_f32_e32 v3, v2, v153
	v_cndmask_b32_e64 v2, v2, v3, s[8:9]
	v_max_f32_e32 v3, v2, v154
	v_cndmask_b32_e64 v2, v2, v3, s[10:11]
	v_max_f32_e32 v3, v2, v155
	v_cndmask_b32_e64 v2, v2, v3, s[14:15]
	v_max_f32_e32 v3, v2, v140
	v_cndmask_b32_e64 v2, v2, v3, s[12:13]
	v_max_f32_e32 v3, v2, v141
	v_cndmask_b32_e64 v2, v2, v3, s[16:17]
	v_max_f32_e32 v3, v2, v142
	v_cndmask_b32_e64 v2, v2, v3, s[18:19]
	v_max_f32_e32 v3, v2, v143
	v_cndmask_b32_e64 v2, v2, v3, s[22:23]
	v_max_f32_e32 v3, v2, v144
	v_cndmask_b32_e64 v2, v2, v3, s[20:21]
	v_max_f32_e32 v3, v2, v145
	v_cndmask_b32_e64 v2, v2, v3, s[24:25]
	v_max_f32_e32 v3, v2, v146
	v_cndmask_b32_e64 v2, v2, v3, s[26:27]
	v_max_f32_e32 v3, v2, v147
	v_cndmask_b32_e64 v2, v2, v3, s[30:31]
	v_max_f32_e32 v3, v2, v148
	v_cndmask_b32_e64 v2, v2, v3, s[28:29]
	v_max_f32_e32 v3, v2, v149
	v_cndmask_b32_e64 v2, v2, v3, s[34:35]
	v_max_f32_e32 v3, v2, v150
	v_cndmask_b32_e64 v2, v2, v3, s[36:37]
	v_max_f32_e32 v156, v151, v151
	v_max_f32_e32 v3, v2, v156
	v_cndmask_b32_e64 v2, v2, v3, s[38:39]
	v_add_f32_e32 v3, 0x41400000, v160
	v_cmp_gt_f32_e32 vcc, v2, v3
	s_cbranch_vccz .LBB0_1016
	v_and_b32_e32 v156, 64, v204
	v_xor_b32_e32 v3, 16, v204
	v_add_u32_e32 v156, 64, v156
	v_cmp_lt_i32_e32 vcc, v3, v156
	v_xor_b32_e32 v157, 32, v204
	s_nop 0
	v_cndmask_b32_e32 v3, v204, v3, vcc
	v_lshlrev_b32_e32 v3, 2, v3
	ds_bpermute_b32 v3, v3, v2
	v_max_f32_e32 v2, v2, v2
	v_cmp_lt_i32_e32 vcc, v157, v156
	s_waitcnt lgkmcnt(0)
	v_max_f32_e32 v3, v3, v3
	v_max_f32_e32 v2, v2, v3
	v_cndmask_b32_e32 v3, v204, v157, vcc
	v_lshlrev_b32_e32 v3, 2, v3
	ds_bpermute_b32 v3, v3, v2
	v_mov_b32_e32 v156, v158
	v_mov_b32_e32 v157, v159
	v_mov_b32_e32 v158, v160
	s_waitcnt lgkmcnt(0)
	v_max3_f32 v3, v160, v2, v3
	v_sub_f32_e32 v2, v160, v3
	v_exp_f32_e32 v2, v2
	v_mov_b32_e32 v158, v3
	v_mov_b32_e32 v160, v3
	v_mul_f32_e32 v167, v167, v2
	v_pk_mul_f32 v[18:19], v[18:19], v[2:3] op_sel_hi:[1,0]
	v_pk_mul_f32 v[16:17], v[16:17], v[2:3] op_sel_hi:[1,0]
	v_pk_mul_f32 v[14:15], v[14:15], v[2:3] op_sel_hi:[1,0]
	v_pk_mul_f32 v[12:13], v[12:13], v[2:3] op_sel_hi:[1,0]
	v_pk_mul_f32 v[10:11], v[10:11], v[2:3] op_sel_hi:[1,0]
	v_pk_mul_f32 v[8:9], v[8:9], v[2:3] op_sel_hi:[1,0]
	v_pk_mul_f32 v[6:7], v[6:7], v[2:3] op_sel_hi:[1,0]
	v_pk_mul_f32 v[4:5], v[4:5], v[2:3] op_sel_hi:[1,0]
	s_branch .LBB0_1017

; #define MFMA16(a, b, c) __builtin_amdgcn_mfma_f32_16x16x32_f16((a), (b), (c), 0, 0, 0)
; __device__ __forceinline__ float shx(float v, int m) { return __shfl_xor(v, m); }
;     ...
;         const int kbN = kbof((it + 1 < nit) ? it + 1 : it);
;         const int nbA = kbN >> 5, nbB = (nbA + 1 <= maxblk) ? nbA + 1 : maxblk;
;         const f32x4 z = {0.f, 0.f, 0.f, 0.f};
; #pragma unroll
;         for (int s_ = 0; s_ < NS; ++s_) {
;             f32x4 s[4];
; #pragma unroll
;             for (int t = 0; t < 4; ++t) { s[t] = MFMA16(ka[2 * t], qf[s_][0], z); s[t] = MFMA16(ka[2 * t + 1], qf[s_][1], s[t]); }
;             if (s_ == NS - 1) {
;                 const half_t* kpA = kf + (size_t)nbA * 2048; const half_t* kpB = kf + (size_t)nbB * 2048;
; #pragma unroll
;                 for (int i = 0; i < 4; ++i) { ka[i] = *(const half8*)(kpA + i * 512); ka[4 + i] = *(const half8*)(kpB + i * 512); }
;             }
;             if (MODE != 1) {
;                 float mx = -1e30f;
; #pragma unroll
;                 for (int t = 0; t < 4; ++t)
; #pragma unroll
;                     for (int r = 0; r < 4; ++r) { if (valid(s_, kbA + 16 * t + 4 * g + r)) mx = fmaxf(mx, s[t][r]); }
;                 if (__ballot(mx > m[s_] + RESC_THR) != 0ull) {
;                     mx = fmaxf(mx, shx(mx, 16)); mx = fmaxf(mx, shx(mx, 32));
;                     const float mn = fmaxf(m[s_], mx); const float corr = __builtin_amdgcn_exp2f(m[s_] - mn); m[s_] = mn; l[s_] = l[s_] * corr;
;                     if (PV) {
; #pragma unroll
;                         for (int dt = 0; dt < 4; ++dt) o[s_][dt] = o[s_][dt] * corr;
;                     }
;                 }
;             }
; __device__ __forceinline__ void b_unit(const ACtx& X, int b, int h6, int fb, int lane) {
;     ...
;     auto valid = [&](int s_, int kf) { return kf <= iqs[s_] && iqs[s_] - kf <= 128; };
.LBB0_1023:
	s_waitcnt vmcnt(0) lgkmcnt(0)
	v_mfma_f32_16x16x32_f16 v[86:89], v[78:81], v[34:37], 0
	flat_load_dwordx4 v[110:113], v[84:85]
	flat_load_dwordx4 v[102:105], v[84:85] offset:1024
	v_add_u32_e32 v147, s55, v166
	v_cmp_ge_i32_e32 vcc, v144, v147
	v_mfma_f32_16x16x32_f16 v[122:125], v[74:77], v[38:41], v[86:89]
	flat_load_dwordx4 v[94:97], v[84:85] offset:2048
	s_nop 1
	flat_load_dwordx4 v[86:89], v[84:85] offset:3072
	flat_load_dwordx4 v[106:109], v[82:83]
	flat_load_dwordx4 v[98:101], v[82:83] offset:1024
	flat_load_dwordx4 v[90:93], v[82:83] offset:2048
	s_nop 0
	flat_load_dwordx4 v[82:85], v[82:83] offset:3072
	v_cmp_gt_i32_e64 s[6:7], v147, v131
	v_mfma_f32_16x16x32_f16 v[114:117], v[70:73], v[34:37], 0
	s_and_b64 s[6:7], vcc, s[6:7]
	v_cmp_gt_i32_e32 vcc, v144, v147
	v_cmp_ge_i32_e64 s[8:9], v147, v131
	v_mfma_f32_16x16x32_f16 v[126:129], v[58:61], v[38:41], v[114:117]
	s_and_b64 s[8:9], vcc, s[8:9]
	v_add_u32_e32 v148, 2, v147
	v_cmp_le_i32_e32 vcc, v148, v144
	s_nop 0
	v_max_f32_e32 v118, 0xf149f2ca, v122
	v_mfma_f32_16x16x32_f16 v[114:117], v[66:69], v[34:37], 0
	v_cndmask_b32_e64 v142, v172, v118, s[6:7]
	v_cmp_gt_i32_e64 s[10:11], v148, v131
	s_and_b64 s[12:13], vcc, s[10:11]
	v_mfma_f32_16x16x32_f16 v[118:121], v[62:65], v[38:41], v[114:117]
	v_add_u32_e32 v149, 3, v147
	v_cmp_le_i32_e32 vcc, v149, v144
	v_cmp_gt_i32_e64 s[10:11], v149, v131
	s_nop 0
	v_max_f32_e32 v143, v142, v123
	v_cndmask_b32_e64 v142, v142, v143, s[8:9]
	v_max_f32_e32 v143, v142, v124
	v_cndmask_b32_e64 v142, v142, v143, s[12:13]
	v_max_f32_e32 v143, v142, v125
	s_and_b64 s[14:15], vcc, s[10:11]
	v_add_u32_e32 v152, 16, v147
	v_cndmask_b32_e64 v142, v142, v143, s[14:15]
	v_cmp_le_i32_e32 vcc, v152, v144
	v_cmp_gt_i32_e64 s[10:11], v152, v131
	v_max_f32_e32 v143, v142, v126
	s_and_b64 s[10:11], vcc, s[10:11]
	v_cndmask_b32_e64 v142, v142, v143, s[10:11]
	v_add_u32_e32 v150, 17, v147
	v_cmp_le_i32_e32 vcc, v150, v144
	v_cmp_gt_i32_e64 s[16:17], v150, v131
	v_max_f32_e32 v143, v142, v127
	s_and_b64 s[16:17], vcc, s[16:17]
	v_cndmask_b32_e64 v142, v142, v143, s[16:17]
	v_add_u32_e32 v151, 18, v147
	v_cmp_le_i32_e32 vcc, v151, v144
	v_cmp_gt_i32_e64 s[18:19], v151, v131
	v_max_f32_e32 v143, v142, v128
	s_and_b64 s[18:19], vcc, s[18:19]
	v_cndmask_b32_e64 v142, v142, v143, s[18:19]
	v_add_u32_e32 v153, 19, v147
	v_cmp_le_i32_e32 vcc, v153, v144
	v_cmp_gt_i32_e64 s[20:21], v153, v131
	v_max_f32_e32 v143, v142, v129
	s_and_b64 s[22:23], vcc, s[20:21]
	v_cndmask_b32_e64 v142, v142, v143, s[22:23]
	v_add_u32_e32 v154, 32, v147
	v_cmp_le_i32_e32 vcc, v154, v144
	v_cmp_gt_i32_e64 s[20:21], v154, v131
	v_max_f32_e32 v143, v142, v118
	s_and_b64 s[20:21], vcc, s[20:21]
	v_cndmask_b32_e64 v142, v142, v143, s[20:21]
	v_add_u32_e32 v155, 33, v147
	v_cmp_le_i32_e32 vcc, v155, v144
	v_cmp_gt_i32_e64 s[24:25], v155, v131
	v_mfma_f32_16x16x32_f16 v[114:117], v[54:57], v[34:37], 0
	v_max_f32_e32 v143, v142, v119
	s_and_b64 s[24:25], vcc, s[24:25]
	v_cndmask_b32_e64 v142, v142, v143, s[24:25]
	v_add_u32_e32 v156, 34, v147
	v_cmp_le_i32_e32 vcc, v156, v144
	v_cmp_gt_i32_e64 s[26:27], v156, v131
	v_max_f32_e32 v143, v142, v120
	s_and_b64 s[26:27], vcc, s[26:27]
	v_mfma_f32_16x16x32_f16 v[114:117], v[50:53], v[38:41], v[114:117]
	v_cndmask_b32_e64 v142, v142, v143, s[26:27]
	v_add_u32_e32 v157, 35, v147
	v_cmp_le_i32_e32 vcc, v157, v144
	v_cmp_gt_i32_e64 s[28:29], v157, v131
	v_max_f32_e32 v143, v142, v121
	s_and_b64 s[30:31], vcc, s[28:29]
	v_cndmask_b32_e64 v142, v142, v143, s[30:31]
	v_add_u32_e32 v158, 48, v147
	v_cmp_le_i32_e32 vcc, v158, v144
	v_cmp_gt_i32_e64 s[28:29], v158, v131
	v_max_f32_e32 v143, v142, v114
	s_and_b64 s[28:29], vcc, s[28:29]
	v_cndmask_b32_e64 v142, v142, v143, s[28:29]
	v_add_u32_e32 v159, 49, v147
	v_cmp_le_i32_e32 vcc, v159, v144
	v_cmp_gt_i32_e64 s[34:35], v159, v131
	v_max_f32_e32 v143, v142, v115
	s_and_b64 s[34:35], vcc, s[34:35]
	v_cndmask_b32_e64 v142, v142, v143, s[34:35]
	v_add_u32_e32 v160, 50, v147
	v_cmp_le_i32_e32 vcc, v160, v144
	v_cmp_gt_i32_e64 s[36:37], v160, v131
	v_max_f32_e32 v143, v142, v116
	s_and_b64 s[36:37], vcc, s[36:37]
	v_cndmask_b32_e64 v142, v142, v143, s[36:37]
	v_add_u32_e32 v161, 51, v147
	v_cmp_le_i32_e32 vcc, v161, v144
	v_cmp_gt_i32_e64 s[38:39], v161, v131
	v_max_f32_e32 v162, v117, v117
	v_max_f32_e32 v143, v142, v162
	s_and_b64 s[38:39], vcc, s[38:39]
	v_cndmask_b32_e64 v142, v142, v143, s[38:39]
	v_add_f32_e32 v143, 0x41400000, v136
	v_cmp_gt_f32_e32 vcc, v142, v143
	s_cbranch_vccz .LBB0_1025
	v_and_b32_e32 v162, 64, v204
	v_xor_b32_e32 v143, 16, v204
	v_add_u32_e32 v162, 64, v162
	v_cmp_lt_i32_e32 vcc, v143, v162
	s_nop 1
	v_cndmask_b32_e32 v143, v204, v143, vcc
	v_lshlrev_b32_e32 v143, 2, v143
	ds_bpermute_b32 v143, v143, v142
	v_max_f32_e32 v142, v142, v142
	s_waitcnt lgkmcnt(0)
	v_max_f32_e32 v143, v143, v143
	v_max_f32_e32 v142, v142, v143
	v_xor_b32_e32 v143, 32, v204
	v_cmp_lt_i32_e32 vcc, v143, v162
	s_nop 1
	v_cndmask_b32_e32 v143, v204, v143, vcc
	v_lshlrev_b32_e32 v143, 2, v143
	ds_bpermute_b32 v143, v143, v142
	s_waitcnt lgkmcnt(0)
	v_max3_f32 v142, v136, v142, v143
	v_sub_f32_e32 v136, v136, v142
	v_exp_f32_e32 v136, v136
	v_mov_b32_e32 v143, v137
	v_mul_f32_e32 v134, v134, v136
	v_pk_mul_f32 v[32:33], v[32:33], v[136:137] op_sel_hi:[1,0]
	v_pk_mul_f32 v[30:31], v[30:31], v[136:137] op_sel_hi:[1,0]
	v_pk_mul_f32 v[28:29], v[28:29], v[136:137] op_sel_hi:[1,0]
	v_pk_mul_f32 v[26:27], v[26:27], v[136:137] op_sel_hi:[1,0]
	v_pk_mul_f32 v[24:25], v[24:25], v[136:137] op_sel_hi:[1,0]
	v_pk_mul_f32 v[22:23], v[22:23], v[136:137] op_sel_hi:[1,0]
	v_pk_mul_f32 v[20:21], v[20:21], v[136:137] op_sel_hi:[1,0]
	v_pk_mul_f32 v[18:19], v[18:19], v[136:137] op_sel_hi:[1,0]
	v_mov_b32_e32 v136, v142
	s_branch .LBB0_1026

; #define MFMA16(a, b, c) __builtin_amdgcn_mfma_f32_16x16x32_f16((a), (b), (c), 0, 0, 0)
;     ...
;             float p[4][4]; float ps = 0.f;
; #pragma unroll
;             for (int t = 0; t < 4; ++t)
; #pragma unroll
;                 for (int r = 0; r < 4; ++r) { p[t][r] = valid(s_, kbA + 16 * t + 4 * g + r) ? __builtin_amdgcn_exp2f(s[t][r] - m[s_]) : 0.f; if (MODE == 1) p[t][r] *= l[s_]; ps += p[t][r]; }
;             if (MODE != 1) l[s_] = l[s_] + ps;
;             if (PV) {
;                 const half8 pfA = {(half_t)p[0][0], (half_t)p[0][1], (half_t)p[0][2], (half_t)p[0][3], (half_t)p[1][0], (half_t)p[1][1], (half_t)p[1][2], (half_t)p[1][3]};
;                 const half8 pfB = {(half_t)p[2][0], (half_t)p[2][1], (half_t)p[2][2], (half_t)p[2][3], (half_t)p[3][0], (half_t)p[3][1], (half_t)p[3][2], (half_t)p[3][3]};
; #pragma unroll
;                 for (int dt = 0; dt < 4; ++dt) { o[s_][dt] = MFMA16(va[dt], pfA, o[s_][dt]); o[s_][dt] = MFMA16(va[4 + dt], pfB, o[s_][dt]); }
.LBB0_1026:
	v_sub_f32_e32 v122, v122, v136
	v_exp_f32_e32 v122, v122
	v_sub_f32_e32 v123, v123, v136
	v_sub_f32_e32 v126, v126, v136
	v_sub_f32_e32 v127, v127, v136
	v_sub_f32_e32 v128, v128, v136
	v_sub_f32_e32 v129, v129, v136
	v_exp_f32_e32 v123, v123
	v_sub_f32_e32 v124, v124, v136
	v_exp_f32_e32 v126, v126
	v_exp_f32_e32 v127, v127
	v_exp_f32_e32 v128, v128
	v_exp_f32_e32 v129, v129
	v_mfma_f32_16x16x32_f16 v[78:81], v[78:81], v[42:45], 0
	v_exp_f32_e32 v124, v124
	v_sub_f32_e32 v125, v125, v136
	v_exp_f32_e32 v125, v125
	v_cndmask_b32_e64 v122, 0, v122, s[6:7]
	v_cndmask_b32_e64 v123, 0, v123, s[8:9]
	v_cndmask_b32_e64 v162, 0, v126, s[10:11]
	v_cndmask_b32_e64 v167, 0, v127, s[16:17]
	v_cndmask_b32_e64 v173, 0, v128, s[18:19]
	v_cndmask_b32_e64 v183, 0, v129, s[22:23]
	v_sub_f32_e32 v114, v114, v136
	v_sub_f32_e32 v115, v115, v136
	v_mfma_f32_16x16x32_f16 v[126:129], v[74:77], v[46:49], v[78:81]
	v_add_f32_e32 v74, 0, v122
	v_cndmask_b32_e64 v124, 0, v124, s[12:13]
	v_exp_f32_e32 v114, v114
	v_exp_f32_e32 v115, v115
	v_sub_f32_e32 v116, v116, v136
	v_sub_f32_e32 v117, v117, v136
	v_add_f32_e32 v74, v123, v74
	v_mfma_f32_16x16x32_f16 v[70:73], v[70:73], v[42:45], 0
	v_cndmask_b32_e64 v125, 0, v125, s[14:15]
	v_sub_f32_e32 v118, v118, v136
	v_exp_f32_e32 v116, v116
	v_exp_f32_e32 v117, v117
	v_add_f32_e32 v74, v124, v74
	v_exp_f32_e32 v118, v118
	v_sub_f32_e32 v119, v119, v136
	v_add_f32_e32 v74, v125, v74
	v_exp_f32_e32 v119, v119
	v_sub_f32_e32 v120, v120, v136
	v_sub_f32_e32 v121, v121, v136
	v_add_f32_e32 v74, v162, v74
	v_exp_f32_e32 v120, v120
	v_exp_f32_e32 v121, v121
	v_cndmask_b32_e64 v190, 0, v114, s[28:29]
	v_cndmask_b32_e64 v191, 0, v115, s[34:35]
	v_cvt_pk_f16_f32 v115, v124, v125
	v_cvt_pk_f16_f32 v114, v122, v123
	v_mfma_f32_16x16x32_f16 v[122:125], v[58:61], v[46:49], v[70:73]
	v_add_f32_e32 v58, v167, v74
	v_cndmask_b32_e64 v192, 0, v116, s[36:37]
	v_cndmask_b32_e64 v193, 0, v117, s[38:39]
	v_cvt_pk_f16_f32 v117, v173, v183
	v_cvt_pk_f16_f32 v116, v162, v167
	s_add_i32 s56, s54, 1
	v_add_f32_e32 v58, v173, v58
	v_cndmask_b32_e64 v186, 0, v118, s[20:21]
	s_waitcnt vmcnt(0) lgkmcnt(0)
; #define MFMA16(a, b, c) __builtin_amdgcn_mfma_f32_16x16x32_f16((a), (b), (c), 0, 0, 0)
; __device__ __forceinline__ float shx(float v, int m) { return __shfl_xor(v, m); }
;     ...
;         for (int s_ = 0; s_ < NS; ++s_) {
;             f32x4 s[4];
; #pragma unroll
;             for (int t = 0; t < 4; ++t) { s[t] = MFMA16(ka[2 * t], qf[s_][0], z); s[t] = MFMA16(ka[2 * t + 1], qf[s_][1], s[t]); }
;             if (s_ == NS - 1) {
;                 const half_t* kpA = kf + (size_t)nbA * 2048; const half_t* kpB = kf + (size_t)nbB * 2048;
; #pragma unroll
;                 for (int i = 0; i < 4; ++i) { ka[i] = *(const half8*)(kpA + i * 512); ka[4 + i] = *(const half8*)(kpB + i * 512); }
;             }
;             if (MODE != 1) {
;                 float mx = -1e30f;
; #pragma unroll
;                 for (int t = 0; t < 4; ++t)
; #pragma unroll
;                     for (int r = 0; r < 4; ++r) { if (valid(s_, kbA + 16 * t + 4 * g + r)) mx = fmaxf(mx, s[t][r]); }
;                 if (__ballot(mx > m[s_] + RESC_THR) != 0ull) {
;                     mx = fmaxf(mx, shx(mx, 16)); mx = fmaxf(mx, shx(mx, 32));
;                     const float mn = fmaxf(m[s_], mx); const float corr = __builtin_amdgcn_exp2f(m[s_] - mn); m[s_] = mn; l[s_] = l[s_] * corr;
;                     if (PV) {
; #pragma unroll
;                         for (int dt = 0; dt < 4; ++dt) o[s_][dt] = o[s_][dt] * corr;
;                     }
;                 }
;             }
;             float p[4][4]; float ps = 0.f;
; #pragma unroll
;             for (int t = 0; t < 4; ++t)
; #pragma unroll
;                 for (int r = 0; r < 4; ++r) { p[t][r] = valid(s_, kbA + 16 * t + 4 * g + r) ? __builtin_amdgcn_exp2f(s[t][r] - m[s_]) : 0.f; if (MODE == 1) p[t][r] *= l[s_]; ps += p[t][r]; }
;             if (MODE != 1) l[s_] = l[s_] + ps;
;             if (PV) {
;                 const half8 pfA = {(half_t)p[0][0], (half_t)p[0][1], (half_t)p[0][2], (half_t)p[0][3], (half_t)p[1][0], (half_t)p[1][1], (half_t)p[1][2], (half_t)p[1][3]};
;                 const half8 pfB = {(half_t)p[2][0], (half_t)p[2][1], (half_t)p[2][2], (half_t)p[2][3], (half_t)p[3][0], (half_t)p[3][1], (half_t)p[3][2], (half_t)p[3][3]};
; #pragma unroll
;                 for (int dt = 0; dt < 4; ++dt) { o[s_][dt] = MFMA16(va[dt], pfA, o[s_][dt]); o[s_][dt] = MFMA16(va[4 + dt], pfB, o[s_][dt]); }
;             }
	v_mfma_f32_16x16x32_f16 v[30:33], v[110:113], v[114:117], v[30:33]
	s_cmp_lt_i32 s54, s53
	v_add_f32_e32 v70, v183, v58
	v_cndmask_b32_e64 v187, 0, v119, s[24:25]
	v_mfma_f32_16x16x32_f16 v[26:29], v[102:105], v[114:117], v[26:29]
	s_cselect_b32 s2, s56, s54
	v_cndmask_b32_e64 v188, 0, v120, s[26:27]
	v_cndmask_b32_e64 v189, 0, v121, s[30:31]
	v_mfma_f32_16x16x32_f16 v[22:25], v[94:97], v[114:117], v[22:25]
	s_lshl_b32 s2, s2, 6
	v_cvt_pk_f16_f32 v121, v192, v193
	v_cvt_pk_f16_f32 v120, v190, v191
	v_mfma_f32_16x16x32_f16 v[18:21], v[86:89], v[114:117], v[18:21]
	v_cvt_pk_f16_f32 v119, v188, v189
	v_cvt_pk_f16_f32 v118, v186, v187
	s_add_i32 s55, s2, s52
	v_mfma_f32_16x16x32_f16 v[58:61], v[66:69], v[42:45], 0
	v_add_f32_e32 v66, v186, v70
	v_add_f32_e32 v66, v187, v66
	v_add_f32_e32 v66, v188, v66
	v_mfma_f32_16x16x32_f16 v[30:33], v[106:109], v[118:121], v[30:33]
	s_lshr_b32 s84, s55, 5
	s_add_i32 s2, s84, 1
	s_min_i32 s6, s2, s43
	v_mfma_f32_16x16x32_f16 v[26:29], v[98:101], v[118:121], v[26:29]
	s_lshl_b64 s[2:3], s[84:85], 12
	s_ashr_i32 s7, s6, 31
	v_lshl_add_u64 v[136:137], v[138:139], 0, s[2:3]
	v_mfma_f32_16x16x32_f16 v[22:25], v[90:93], v[118:121], v[22:25]
	s_lshl_b64 s[48:49], s[6:7], 12
	v_lshl_add_u64 v[184:185], v[138:139], 0, s[48:49]
	v_cmp_le_i32_e32 vcc, v147, v145
	v_mfma_f32_16x16x32_f16 v[18:21], v[82:85], v[118:121], v[18:21]
	v_cmp_gt_i32_e64 s[6:7], v147, v146
	s_and_b64 s[38:39], vcc, s[6:7]
	v_cmp_lt_i32_e32 vcc, v147, v145
	v_mfma_f32_16x16x32_f16 v[118:121], v[62:65], v[46:49], v[58:61]
	v_cmp_ge_i32_e64 s[6:7], v147, v146
	s_and_b64 s[36:37], vcc, s[6:7]
	v_cmp_le_i32_e32 vcc, v148, v145
	v_add_f32_e32 v58, v189, v66
	v_add_f32_e32 v58, v190, v58
	v_mfma_f32_16x16x32_f16 v[54:57], v[54:57], v[42:45], 0
	v_add_f32_e32 v58, v191, v58
	v_add_f32_e32 v58, v192, v58
	v_add_f32_e32 v58, v193, v58
	v_add_f32_e32 v134, v134, v58
	v_mfma_f32_16x16x32_f16 v[114:117], v[50:53], v[46:49], v[54:57]
	flat_load_dwordx4 v[78:81], v[136:137]
	flat_load_dwordx4 v[74:77], v[136:137] offset:1024
	flat_load_dwordx4 v[66:69], v[184:185]
	flat_load_dwordx4 v[62:65], v[184:185] offset:1024
	flat_load_dwordx4 v[70:73], v[136:137] offset:2048
	flat_load_dwordx4 v[58:61], v[136:137] offset:3072
	flat_load_dwordx4 v[54:57], v[184:185] offset:2048
	flat_load_dwordx4 v[50:53], v[184:185] offset:3072
	v_max_f32_e32 v136, 0xf149f2ca, v126
	v_cndmask_b32_e64 v136, v172, v136, s[38:39]
	v_max_f32_e32 v137, v136, v127
	v_cndmask_b32_e64 v136, v136, v137, s[36:37]
	v_cmp_gt_i32_e64 s[6:7], v148, v146
	v_max_f32_e32 v137, v136, v128
	s_and_b64 s[34:35], vcc, s[6:7]
	v_cndmask_b32_e64 v136, v136, v137, s[34:35]
	v_cmp_le_i32_e32 vcc, v149, v145
	v_cmp_gt_i32_e64 s[6:7], v149, v146
	v_max_f32_e32 v137, v136, v129
	s_and_b64 s[28:29], vcc, s[6:7]
	v_cndmask_b32_e64 v136, v136, v137, s[28:29]
	v_sub_u32_e32 v137, v144, v147
	s_movk_i32 s6, 0x81
	v_cmp_le_i32_e32 vcc, v152, v145
	v_cmp_gt_i32_e64 s[6:7], s6, v137
	v_max_f32_e32 v137, v136, v122
	s_and_b64 s[30:31], vcc, s[6:7]
	v_cndmask_b32_e64 v136, v136, v137, s[30:31]
	v_cmp_le_i32_e32 vcc, v150, v145
	v_cmp_gt_i32_e64 s[6:7], v150, v146
	v_max_f32_e32 v137, v136, v123
	s_and_b64 s[26:27], vcc, s[6:7]
	v_cndmask_b32_e64 v136, v136, v137, s[26:27]
	v_cmp_le_i32_e32 vcc, v151, v145
	v_cmp_gt_i32_e64 s[6:7], v151, v146
	v_max_f32_e32 v137, v136, v124
	s_and_b64 s[24:25], vcc, s[6:7]
	v_cndmask_b32_e64 v136, v136, v137, s[24:25]
	v_cmp_le_i32_e32 vcc, v153, v145
	v_cmp_gt_i32_e64 s[6:7], v153, v146
	v_max_f32_e32 v137, v136, v125
	s_and_b64 s[20:21], vcc, s[6:7]
	v_cndmask_b32_e64 v136, v136, v137, s[20:21]
	v_cmp_le_i32_e32 vcc, v154, v145
	v_cmp_gt_i32_e64 s[6:7], v154, v146
	v_max_f32_e32 v137, v136, v118
	s_and_b64 s[22:23], vcc, s[6:7]
	v_cndmask_b32_e64 v136, v136, v137, s[22:23]
	v_cmp_le_i32_e32 vcc, v155, v145
	v_cmp_gt_i32_e64 s[6:7], v155, v146
	v_max_f32_e32 v137, v136, v119
	s_and_b64 s[18:19], vcc, s[6:7]
	v_cndmask_b32_e64 v136, v136, v137, s[18:19]
	v_cmp_le_i32_e32 vcc, v156, v145
	v_cmp_gt_i32_e64 s[6:7], v156, v146
	v_max_f32_e32 v137, v136, v120
	s_and_b64 s[16:17], vcc, s[6:7]
	v_cndmask_b32_e64 v136, v136, v137, s[16:17]
	v_cmp_le_i32_e32 vcc, v157, v145
	v_cmp_gt_i32_e64 s[6:7], v157, v146
	v_max_f32_e32 v137, v136, v121
	s_and_b64 s[12:13], vcc, s[6:7]
	v_cndmask_b32_e64 v136, v136, v137, s[12:13]
	v_cmp_le_i32_e32 vcc, v158, v145
	v_cmp_gt_i32_e64 s[6:7], v158, v146
	v_max_f32_e32 v137, v136, v114
	s_and_b64 s[14:15], vcc, s[6:7]
	v_cndmask_b32_e64 v136, v136, v137, s[14:15]
	v_cmp_le_i32_e32 vcc, v159, v145
	v_cmp_gt_i32_e64 s[6:7], v159, v146
	v_max_f32_e32 v137, v136, v115
	s_and_b64 s[10:11], vcc, s[6:7]
	v_cndmask_b32_e64 v136, v136, v137, s[10:11]
	v_cmp_le_i32_e32 vcc, v160, v145
	v_cmp_gt_i32_e64 s[6:7], v160, v146
	v_max_f32_e32 v137, v136, v116
	s_and_b64 s[8:9], vcc, s[6:7]
	v_cndmask_b32_e64 v136, v136, v137, s[8:9]
	v_cmp_le_i32_e32 vcc, v161, v145
	v_cmp_gt_i32_e64 s[6:7], v161, v146
	v_max_f32_e32 v147, v117, v117
	v_max_f32_e32 v137, v136, v147
	s_and_b64 s[6:7], vcc, s[6:7]
	v_cndmask_b32_e64 v136, v136, v137, s[6:7]
	v_add_f32_e32 v137, 0x41400000, v143
	v_cmp_gt_f32_e32 vcc, v136, v137
	s_cbranch_vccz .LBB0_1028
	v_and_b32_e32 v147, 64, v204
	v_xor_b32_e32 v137, 16, v204
	v_add_u32_e32 v147, 64, v147
	v_cmp_lt_i32_e32 vcc, v137, v147
	s_nop 1
	v_cndmask_b32_e32 v137, v204, v137, vcc
	v_lshlrev_b32_e32 v137, 2, v137
	ds_bpermute_b32 v137, v137, v136
	v_max_f32_e32 v136, v136, v136
	s_waitcnt lgkmcnt(0)
	v_max_f32_e32 v137, v137, v137
	v_max_f32_e32 v136, v136, v137
	v_xor_b32_e32 v137, 32, v204
	v_cmp_lt_i32_e32 vcc, v137, v147
	s_nop 1
	v_cndmask_b32_e32 v137, v204, v137, vcc
	v_lshlrev_b32_e32 v137, 2, v137
	ds_bpermute_b32 v137, v137, v136
	s_waitcnt lgkmcnt(0)
	v_max3_f32 v147, v143, v136, v137
	v_sub_f32_e32 v136, v143, v147
	v_exp_f32_e32 v148, v136
	v_mov_b32_e32 v143, v147
	v_mov_b64_e32 v[136:137], v[142:143]
	v_mul_f32_e32 v135, v135, v148
	v_pk_mul_f32 v[16:17], v[16:17], v[148:149] op_sel_hi:[1,0]
	v_pk_mul_f32 v[14:15], v[14:15], v[148:149] op_sel_hi:[1,0]
	v_pk_mul_f32 v[12:13], v[12:13], v[148:149] op_sel_hi:[1,0]
	v_pk_mul_f32 v[10:11], v[10:11], v[148:149] op_sel_hi:[1,0]
	v_pk_mul_f32 v[8:9], v[8:9], v[148:149] op_sel_hi:[1,0]
	v_pk_mul_f32 v[6:7], v[6:7], v[148:149] op_sel_hi:[1,0]
	v_pk_mul_f32 v[4:5], v[4:5], v[148:149] op_sel_hi:[1,0]
	v_pk_mul_f32 v[2:3], v[2:3], v[148:149] op_sel_hi:[1,0]
	s_branch .LBB0_1029
